# stack plus EW loops: first wait only covers the Y and first x loads, hoisted x loads waited for at first use
# baseline (speedup 1.0000x reference)
; __device__ __forceinline__ void ew_post(const bf16* Y, const float* xin, float* xout, const float* gpost, const float* gnext, bf16* H, int gw, int ngw, int lane) {
;     for (int m0 = EW_NR * gw; m0 < NTOK; m0 += EW_NR * ngw) {
;         f32x4 y[EW_NR][4], xv[EW_NR][4]; float s[EW_NR];
; #pragma unroll
;         for (int q = 0; q < EW_NR; ++q) { const v2u* yr = (const v2u*)(Y + (size_t)(m0 + q) * DM) + lane; const f32x4* xr = (const f32x4*)(xin + (size_t)(m0 + q) * DM) + lane;
; #pragma unroll
;             for (int j = 0; j < 4; ++j) { const v2u w = __builtin_nontemporal_load(yr + 64 * j); y[q][j] = (f32x4){bf_lo(w.x), bf_hi(w.x), bf_lo(w.y), bf_hi(w.y)}; xv[q][j] = __builtin_nontemporal_load(xr + 64 * j); } }
.LBB0_191:
	global_load_dwordx2 v[16:17], v[68:69], off offset:-4096 nt
	global_load_dwordx2 v[18:19], v[68:69], off offset:-2048 nt
	global_load_dwordx2 v[20:21], v[68:69], off nt
	v_add_co_u32_e32 v0, vcc, 0xfffff000, v68
	s_movk_i32 s4, 0xf000
	s_nop 0
	v_addc_co_u32_e32 v1, vcc, -1, v69, vcc
	global_load_dwordx2 v[22:23], v[0:1], off offset:-2048 nt
	global_load_dwordx2 v[24:25], v[0:1], off offset:-3584 nt
	global_load_dwordx2 v[26:27], v[0:1], off offset:-3072 nt
	global_load_dwordx2 v[28:29], v[0:1], off offset:-2560 nt
	global_load_dwordx2 v[30:31], v[0:1], off offset:-1536 nt
	global_load_dwordx2 v[42:43], v[68:69], off offset:-3584 nt
	global_load_dwordx2 v[84:85], v[68:69], off offset:-3072 nt
	global_load_dwordx2 v[94:95], v[68:69], off offset:-2560 nt
	global_load_dwordx4 v[4:7], v[70:71], off offset:-3072 nt
	global_load_dwordx2 v[38:39], v[0:1], off offset:-1024 nt
	global_load_dwordx2 v[46:47], v[68:69], off offset:-1536 nt
	global_load_dwordx2 v[86:87], v[68:69], off offset:-1024 nt
	global_load_dwordx2 v[88:89], v[68:69], off offset:-512 nt
	global_load_dwordx2 v[40:41], v[0:1], off offset:-512 nt
	v_add_co_u32_e32 v36, vcc, s4, v70
	s_movk_i32 s6, 0xe000
	s_nop 0
	v_addc_co_u32_e32 v37, vcc, -1, v71, vcc
	v_add_co_u32_e32 v48, vcc, 0xffffd000, v70
	s_mov_b64 s[4:5], vcc
	v_addc_co_u32_e64 v49, s[4:5], -1, v71, s[4:5]
	global_load_dwordx4 v[0:3], v[48:49], off offset:-3072 nt
	v_add_co_u32_e32 v50, vcc, s6, v70
	global_load_dwordx4 v[8:11], v[36:37], off offset:-3072 nt
	s_nop 0
	v_addc_co_u32_e32 v51, vcc, -1, v71, vcc
	global_load_dwordx4 v[12:15], v[50:51], off offset:-3072 nt
	global_load_dwordx4 v[124:127], v[48:49], off offset:-2048 nt
	global_load_dwordx4 v[128:131], v[50:51], off offset:-2048 nt
	global_load_dwordx4 v[132:135], v[36:37], off offset:-2048 nt
	global_load_dwordx4 v[136:139], v[70:71], off offset:-2048 nt
	global_load_dwordx4 v[140:143], v[48:49], off offset:-1024 nt
	global_load_dwordx4 v[144:147], v[50:51], off offset:-1024 nt
	global_load_dwordx4 v[148:151], v[36:37], off offset:-1024 nt
	global_load_dwordx4 v[152:155], v[70:71], off offset:-1024 nt
	global_load_dwordx4 v[156:159], v[48:49], off nt
	global_load_dwordx4 v[160:163], v[70:71], off offset:-4096 nt
	global_load_dwordx4 v[164:167], v[50:51], off nt
	global_load_dwordx4 v[168:171], v[70:71], off nt
	s_waitcnt vmcnt(12)
	v_lshlrev_b32_e32 v79, 16, v22
	v_and_b32_e32 v59, 0xffff0000, v22
	v_lshlrev_b32_e32 v60, 16, v23
	v_and_b32_e32 v61, 0xffff0000, v23
	v_lshlrev_b32_e32 v54, 16, v17
	v_and_b32_e32 v55, 0xffff0000, v17
	v_lshlrev_b32_e32 v72, 16, v19
	v_and_b32_e32 v73, 0xffff0000, v19
	v_and_b32_e32 v17, 0xffff0000, v24
	v_and_b32_e32 v19, 0xffff0000, v25
	v_lshlrev_b32_e32 v83, 16, v16
	v_and_b32_e32 v53, 0xffff0000, v16
	v_lshlrev_b32_e32 v81, 16, v18
	v_and_b32_e32 v63, 0xffff0000, v18
	v_lshlrev_b32_e32 v16, 16, v24
	v_lshlrev_b32_e32 v18, 16, v25
	v_and_b32_e32 v23, 0xffff0000, v27
	v_and_b32_e32 v22, 0xffff0000, v26
	v_lshlrev_b32_e32 v32, 16, v28
	v_and_b32_e32 v33, 0xffff0000, v28
	v_mul_f32_e32 v24, v19, v19
	v_mul_f32_e32 v28, v17, v17
	v_mov_b32_e32 v25, v79
	v_lshlrev_b32_e32 v77, 16, v20
	v_and_b32_e32 v57, 0xffff0000, v20
	v_lshlrev_b32_e32 v74, 16, v21
	v_and_b32_e32 v75, 0xffff0000, v21
	v_lshlrev_b32_e32 v21, 16, v27
	v_lshlrev_b32_e32 v20, 16, v26
	v_lshlrev_b32_e32 v34, 16, v29
	v_and_b32_e32 v35, 0xffff0000, v29
	v_pk_mul_f32 v[26:27], v[22:23], v[22:23]
	v_pk_fma_f32 v[90:91], v[18:19], v[18:19], v[24:25] op_sel_hi:[1,1,0]
	v_pk_fma_f32 v[28:29], v[16:17], v[16:17], v[28:29] op_sel_hi:[1,1,0]
	v_mul_f32_e32 v44, v33, v33
	v_mul_f32_e32 v52, v35, v35
	v_pk_fma_f32 v[26:27], v[20:21], v[20:21], v[26:27]
	v_mov_b32_e32 v78, v28
	v_mov_b32_e32 v24, v90
	v_mul_f32_e32 v56, v59, v59
	v_mul_f32_e32 v58, v60, v60
	v_mul_f32_e32 v62, v61, v61
	v_pk_fma_f32 v[44:45], v[32:33], v[32:33], v[44:45] op_sel_hi:[1,1,0]
	v_pk_fma_f32 v[92:93], v[34:35], v[34:35], v[52:53] op_sel_hi:[1,1,0]
	v_pk_add_f32 v[28:29], v[28:29], v[90:91]
	v_pk_add_f32 v[26:27], v[26:27], v[26:27] op_sel:[0,1] op_sel_hi:[1,0]
	v_pk_mul_f32 v[24:25], v[78:79], v[24:25]
	v_mov_b32_e32 v45, v58
	v_mov_b32_e32 v27, v56
	v_mov_b32_e32 v29, v25
	v_mov_b32_e32 v93, v62
	v_pk_add_f32 v[24:25], v[28:29], v[26:27]
	v_pk_add_f32 v[26:27], v[44:45], v[92:93]
	v_and_b32_e32 v45, 0xffff0000, v30
	v_and_b32_e32 v93, 0xffff0000, v31
	v_pk_add_f32 v[102:103], v[24:25], v[26:27]
	v_lshlrev_b32_e32 v44, 16, v30
	v_lshlrev_b32_e32 v92, 16, v31
	v_mul_f32_e32 v24, v93, v93
	v_and_b32_e32 v27, 0xffff0000, v39
	v_and_b32_e32 v26, 0xffff0000, v38
	v_mul_f32_e32 v52, v45, v45
	v_pk_fma_f32 v[28:29], v[92:93], v[92:93], v[24:25] op_sel_hi:[1,1,0]
	v_lshlrev_b32_e32 v25, 16, v39
	v_lshlrev_b32_e32 v24, 16, v38
	v_pk_mul_f32 v[30:31], v[26:27], v[26:27]
	v_pk_fma_f32 v[90:91], v[44:45], v[44:45], v[52:53] op_sel_hi:[1,1,0]
	v_pk_fma_f32 v[30:31], v[24:25], v[24:25], v[30:31]
	v_mov_b32_e32 v82, v90
	v_mov_b32_e32 v96, v28
	v_mov_b32_e32 v97, v83
	v_mul_f32_e32 v56, v53, v53
	v_pk_add_f32 v[28:29], v[90:91], v[28:29]
	v_pk_mul_f32 v[90:91], v[82:83], v[96:97]
	v_pk_add_f32 v[30:31], v[30:31], v[30:31] op_sel:[0,1] op_sel_hi:[1,0]
	v_lshlrev_b32_e32 v38, 16, v40
	v_and_b32_e32 v39, 0xffff0000, v40
	v_lshlrev_b32_e32 v40, 16, v41
	v_and_b32_e32 v41, 0xffff0000, v41
	v_mov_b32_e32 v29, v91
	v_mov_b32_e32 v31, v56
	v_pk_add_f32 v[28:29], v[28:29], v[30:31]
	v_mul_f32_e32 v30, v39, v39
	v_mul_f32_e32 v52, v41, v41
	v_mul_f32_e32 v58, v54, v54
	v_mul_f32_e32 v62, v55, v55
	v_pk_fma_f32 v[30:31], v[38:39], v[38:39], v[30:31] op_sel_hi:[1,1,0]
	v_pk_fma_f32 v[90:91], v[40:41], v[40:41], v[52:53] op_sel_hi:[1,1,0]
; __device__ __forceinline__ void ew_post(const bf16* Y, const float* xin, float* xout, const float* gpost, const float* gnext, bf16* H, int gw, int ngw, int lane) {
;     ...
;         for (int q = 0; q < EW_NR; ++q) { s[q] = 0.f;
; #pragma unroll
;             for (int j = 0; j < 4; ++j) s[q] += (y[q][j].x * y[q][j].x + y[q][j].y * y[q][j].y) + (y[q][j].z * y[q][j].z + y[q][j].w * y[q][j].w); }
;         float rstd[EW_NR], s2[EW_NR];
; #pragma unroll
;         for (int q = 0; q < EW_NR; ++q) { rstd[q] = rsqrtf(wave_sum(s[q]) * (1.f / DM) + RMS_EPS); s2[q] = 0.f; }
	v_mov_b32_e32 v31, v58
	v_mov_b32_e32 v91, v62
	v_pk_add_f32 v[30:31], v[30:31], v[90:91]
	v_and_b32_e32 v97, 0xffff0000, v43
	v_pk_add_f32 v[114:115], v[28:29], v[30:31]
	v_and_b32_e32 v91, 0xffff0000, v42
	v_lshlrev_b32_e32 v96, 16, v43
	v_mul_f32_e32 v28, v97, v97
	v_and_b32_e32 v31, 0xffff0000, v85
	v_and_b32_e32 v30, 0xffff0000, v84
	v_lshlrev_b32_e32 v90, 16, v42
	v_pk_fma_f32 v[98:99], v[96:97], v[96:97], v[28:29] op_sel_hi:[1,1,0]
	v_lshlrev_b32_e32 v29, 16, v85
	v_lshlrev_b32_e32 v28, 16, v84
	v_pk_mul_f32 v[42:43], v[30:31], v[30:31]
	v_mul_f32_e32 v52, v91, v91
	v_pk_fma_f32 v[100:101], v[28:29], v[28:29], v[42:43]
	v_lshlrev_b32_e32 v42, 16, v94
	v_and_b32_e32 v43, 0xffff0000, v94
	v_lshlrev_b32_e32 v84, 16, v95
	v_and_b32_e32 v85, 0xffff0000, v95
	v_pk_fma_f32 v[94:95], v[90:91], v[90:91], v[52:53] op_sel_hi:[1,1,0]
	v_mov_b32_e32 v110, v98
	v_mov_b32_e32 v80, v94
	v_mov_b32_e32 v111, v81
	v_pk_add_f32 v[94:95], v[94:95], v[98:99]
	v_pk_mul_f32 v[98:99], v[80:81], v[110:111]
	s_nop 1
	v_mov_b32_e32 v110, v192
	v_mov_b32_e32 v111, v193
	v_mov_b32_e32 v112, v194
	v_mov_b32_e32 v113, v195
	v_mul_f32_e32 v56, v63, v63
	v_mov_b32_e32 v95, v99
	v_pk_add_f32 v[98:99], v[100:101], v[100:101] op_sel:[0,1] op_sel_hi:[1,0]
	v_mul_f32_e32 v52, v43, v43
	v_mov_b32_e32 v99, v56
	v_pk_add_f32 v[94:95], v[94:95], v[98:99]
	v_pk_fma_f32 v[98:99], v[42:43], v[42:43], v[52:53] op_sel_hi:[1,1,0]
	v_mul_f32_e32 v52, v85, v85
	v_mul_f32_e32 v58, v72, v72
	v_mul_f32_e32 v62, v73, v73
	v_pk_fma_f32 v[100:101], v[84:85], v[84:85], v[52:53] op_sel_hi:[1,1,0]
	v_mov_b32_e32 v99, v58
	v_mov_b32_e32 v101, v62
	v_pk_add_f32 v[98:99], v[98:99], v[100:101]
	v_and_b32_e32 v101, 0xffff0000, v47
	v_pk_add_f32 v[116:117], v[94:95], v[98:99]
	v_and_b32_e32 v99, 0xffff0000, v46
	v_lshlrev_b32_e32 v98, 16, v46
	v_lshlrev_b32_e32 v100, 16, v47
	v_mul_f32_e32 v46, v101, v101
	v_mul_f32_e32 v52, v99, v99
	v_pk_fma_f32 v[118:119], v[100:101], v[100:101], v[46:47] op_sel_hi:[1,1,0]
	v_pk_fma_f32 v[122:123], v[98:99], v[98:99], v[52:53] op_sel_hi:[1,1,0]
	v_and_b32_e32 v95, 0xffff0000, v87
	v_mov_b32_e32 v76, v122
	v_pk_add_f32 v[122:123], v[122:123], v[118:119]
	v_mov_b32_e32 v119, v77
	v_pk_mul_f32 v[118:119], v[76:77], v[118:119]
	v_and_b32_e32 v94, 0xffff0000, v86
	v_mov_b32_e32 v123, v119
	v_mov_b32_e32 v118, v114
	v_mov_b32_e32 v119, v102
	v_mov_b32_e32 v102, v115
	v_pk_add_f32 v[102:103], v[118:119], v[102:103]
	ds_bpermute_b32 v115, v104, v103
	ds_bpermute_b32 v114, v104, v102
	v_lshlrev_b32_e32 v47, 16, v87
	v_lshlrev_b32_e32 v46, 16, v86
	v_pk_mul_f32 v[86:87], v[94:95], v[94:95]
	v_mul_f32_e32 v56, v57, v57
	v_pk_fma_f32 v[120:121], v[46:47], v[46:47], v[86:87]
	v_and_b32_e32 v87, 0xffff0000, v88
	s_waitcnt lgkmcnt(0)
	v_pk_add_f32 v[102:103], v[102:103], v[114:115]
	v_lshlrev_b32_e32 v86, 16, v88
	v_lshlrev_b32_e32 v88, 16, v89
	v_and_b32_e32 v89, 0xffff0000, v89
	v_pk_add_f32 v[118:119], v[120:121], v[120:121] op_sel:[0,1] op_sel_hi:[1,0]
	ds_bpermute_b32 v115, v105, v103
	ds_bpermute_b32 v114, v105, v102
	v_mul_f32_e32 v52, v87, v87
	v_mov_b32_e32 v119, v56
	v_pk_fma_f32 v[120:121], v[86:87], v[86:87], v[52:53] op_sel_hi:[1,1,0]
	v_mul_f32_e32 v52, v89, v89
	v_mul_f32_e32 v58, v74, v74
	v_mul_f32_e32 v62, v75, v75
	v_pk_add_f32 v[118:119], v[122:123], v[118:119]
	v_pk_fma_f32 v[122:123], v[88:89], v[88:89], v[52:53] op_sel_hi:[1,1,0]
	v_mov_b32_e32 v121, v58
	v_mov_b32_e32 v123, v62
	v_pk_add_f32 v[120:121], v[120:121], v[122:123]
	s_waitcnt lgkmcnt(0)
	v_pk_add_f32 v[102:103], v[102:103], v[114:115]
	v_pk_add_f32 v[118:119], v[118:119], v[120:121]
	ds_bpermute_b32 v115, v106, v103
	ds_bpermute_b32 v114, v106, v102
	v_mov_b32_e32 v120, v118
	v_mov_b32_e32 v121, v116
	v_mov_b32_e32 v116, v119
	v_pk_add_f32 v[116:117], v[120:121], v[116:117]
	ds_bpermute_b32 v119, v104, v117
	ds_bpermute_b32 v118, v104, v116
	s_waitcnt lgkmcnt(2)
	v_pk_add_f32 v[102:103], v[102:103], v[114:115]
	ds_bpermute_b32 v115, v107, v103
	ds_bpermute_b32 v114, v107, v102
	v_mov_b32_e32 v62, v81
	s_waitcnt lgkmcnt(2)
	v_pk_add_f32 v[118:119], v[116:117], v[118:119]
	ds_bpermute_b32 v121, v105, v119
	ds_bpermute_b32 v120, v105, v118
	s_waitcnt lgkmcnt(2)
	v_pk_add_f32 v[102:103], v[102:103], v[114:115]
	ds_bpermute_b32 v115, v108, v103
	ds_bpermute_b32 v114, v108, v102
	s_waitcnt lgkmcnt(2)
	v_pk_add_f32 v[118:119], v[118:119], v[120:121]
	ds_bpermute_b32 v121, v106, v119
	ds_bpermute_b32 v120, v106, v118
	s_waitcnt lgkmcnt(2)
	v_pk_add_f32 v[102:103], v[102:103], v[114:115]
	ds_bpermute_b32 v123, v109, v103
	ds_bpermute_b32 v122, v109, v102
	s_waitcnt vmcnt(0)
	s_nop 1
	v_mov_b32_e32 v114, v124
	v_mov_b32_e32 v115, v125
	v_mov_b32_e32 v116, v126
	v_mov_b32_e32 v117, v127
	s_waitcnt lgkmcnt(2)
	v_pk_add_f32 v[118:119], v[118:119], v[120:121]
	ds_bpermute_b32 v121, v107, v119
	ds_bpermute_b32 v120, v107, v118
	s_waitcnt lgkmcnt(2)
	v_pk_add_f32 v[102:103], v[102:103], v[122:123]
	v_mov_b64_e32 v[122:123], s[24:25]
	v_pk_fma_f32 v[102:103], v[102:103], s[44:45], v[122:123] op_sel_hi:[1,0,0]
	s_waitcnt lgkmcnt(0)
	v_pk_add_f32 v[118:119], v[118:119], v[120:121]
	v_mul_f32_e32 v52, 0x4b800000, v103
	v_cmp_gt_f32_e32 vcc, s3, v103
	ds_bpermute_b32 v121, v108, v119
	ds_bpermute_b32 v120, v108, v118
	v_cndmask_b32_e32 v52, v103, v52, vcc
	v_rsq_f32_e32 v52, v52
	v_mul_f32_e32 v56, 0x4b800000, v102
	v_cmp_gt_f32_e64 s[4:5], s3, v102
	v_mul_f32_e32 v58, 0x45800000, v52
	s_nop 0
	v_cndmask_b32_e64 v56, v102, v56, s[4:5]
	s_waitcnt lgkmcnt(0)
; __device__ __forceinline__ void ew_post(const bf16* Y, const float* xin, float* xout, const float* gpost, const float* gnext, bf16* H, int gw, int ngw, int lane) {
;     ...
;         for (int q = 0; q < EW_NR; ++q) { rstd[q] = rsqrtf(wave_sum(s[q]) * (1.f / DM) + RMS_EPS); s2[q] = 0.f; }
; #pragma unroll
;         for (int j = 0; j < 4; ++j) { const f32x4 g = *((const f32x4*)gpost + lane + 64 * j);
; #pragma unroll
;             for (int q = 0; q < EW_NR; ++q) { xv[q][j] = xv[q][j] + y[q][j] * rstd[q] * g; __builtin_nontemporal_store(xv[q][j], (f32x4*)(xout + (size_t)(m0 + q) * DM) + lane + 64 * j);
	v_pk_add_f32 v[102:103], v[118:119], v[120:121]
	v_cndmask_b32_e32 v76, v52, v58, vcc
	v_rsq_f32_e32 v52, v56
	ds_bpermute_b32 v119, v109, v103
	ds_bpermute_b32 v118, v109, v102
	v_pk_mul_f32 v[16:17], v[76:77], v[16:17] op_sel_hi:[0,1]
	v_pk_fma_f32 v[0:1], v[16:17], v[110:111], v[0:1]
	v_mul_f32_e32 v16, 0x45800000, v52
	v_cndmask_b32_e64 v78, v52, v16, s[4:5]
	s_waitcnt lgkmcnt(0)
	v_pk_add_f32 v[16:17], v[102:103], v[118:119]
	v_pk_mul_f32 v[18:19], v[76:77], v[18:19] op_sel_hi:[0,1]
	v_pk_fma_f32 v[16:17], v[16:17], s[44:45], v[122:123] op_sel_hi:[1,0,0]
	v_pk_fma_f32 v[2:3], v[18:19], v[112:113], v[2:3]
	v_mul_f32_e32 v18, 0x4b800000, v17
	v_cmp_gt_f32_e32 vcc, s3, v17
	s_nop 1
	v_mov_b32_e32 v118, v128
	v_mov_b32_e32 v119, v129
	v_mov_b32_e32 v120, v130
	v_mov_b32_e32 v121, v131
	v_pk_mul_f32 v[34:35], v[76:77], v[34:35] op_sel_hi:[0,1]
	v_cndmask_b32_e32 v17, v17, v18, vcc
	v_rsq_f32_e32 v17, v17
	v_pk_mul_f32 v[18:19], v[78:79], v[44:45] op_sel_hi:[0,1]
	v_pk_fma_f32 v[12:13], v[18:19], v[110:111], v[12:13]
	v_pk_mul_f32 v[44:45], v[78:79], v[92:93] op_sel_hi:[0,1]
	v_mul_f32_e32 v18, 0x45800000, v17
	v_cndmask_b32_e32 v80, v17, v18, vcc
	v_mul_f32_e32 v17, 0x4b800000, v16
	v_cmp_gt_f32_e32 vcc, s3, v16
	v_pk_fma_f32 v[14:15], v[44:45], v[112:113], v[14:15]
	v_pk_mul_f32 v[18:19], v[80:81], v[96:97] op_sel_hi:[0,1]
	v_cndmask_b32_e32 v16, v16, v17, vcc
	v_rsq_f32_e32 v44, v16
	v_pk_mul_f32 v[16:17], v[80:81], v[90:91] op_sel_hi:[0,1]
	s_nop 1
	v_mov_b32_e32 v90, v132
	v_mov_b32_e32 v91, v133
	v_mov_b32_e32 v92, v134
	v_mov_b32_e32 v93, v135
	v_pk_fma_f32 v[16:17], v[110:111], v[16:17], v[8:9]
	v_mul_f32_e32 v8, 0x45800000, v44
	v_cndmask_b32_e32 v82, v44, v8, vcc
	v_pk_fma_f32 v[18:19], v[112:113], v[18:19], v[10:11]
	v_pk_mul_f32 v[8:9], v[82:83], v[98:99] op_sel_hi:[0,1]
	v_pk_mul_f32 v[10:11], v[82:83], v[100:101] op_sel_hi:[0,1]
	global_store_dwordx4 v[48:49], v[0:3], off offset:-3072 sc0 sc1 nt
	global_store_dwordx4 v[50:51], v[12:15], off offset:-3072 sc0 sc1 nt
	global_store_dwordx4 v[36:37], v[16:19], off offset:-3072 sc0 sc1 nt
	v_pk_fma_f32 v[6:7], v[112:113], v[10:11], v[6:7]
	v_pk_fma_f32 v[4:5], v[110:111], v[8:9], v[4:5]
	s_nop 1
	v_mov_b32_e32 v96, v136
	v_mov_b32_e32 v97, v137
	v_mov_b32_e32 v98, v138
	v_mov_b32_e32 v99, v139
	v_mov_b32_e32 v8, v21
	global_store_dwordx4 v[70:71], v[4:7], off offset:-3072 sc0 sc1 nt
	s_nop 1
	v_mov_b32_e32 v100, v196
	v_mov_b32_e32 v101, v197
	v_mov_b32_e32 v102, v198
	v_mov_b32_e32 v103, v199
	s_nop 1
	v_mov_b32_e32 v110, v140
	v_mov_b32_e32 v111, v141
	v_mov_b32_e32 v112, v142
	v_mov_b32_e32 v113, v143
	v_mov_b32_e32 v9, v23
	v_mov_b32_e32 v21, v22
	v_pk_mul_f32 v[10:11], v[76:77], v[8:9] op_sel_hi:[0,1]
	v_pk_mul_f32 v[8:9], v[76:77], v[20:21] op_sel_hi:[0,1]
	v_mov_b32_e32 v20, v25
	v_mov_b32_e32 v21, v27
	v_mov_b32_e32 v25, v26
	v_pk_mul_f32 v[22:23], v[78:79], v[20:21] op_sel_hi:[0,1]
	v_pk_mul_f32 v[20:21], v[78:79], v[24:25] op_sel_hi:[0,1]
	v_mov_b32_e32 v24, v29
	v_mov_b32_e32 v25, v31
	v_mov_b32_e32 v29, v30
	v_pk_mul_f32 v[26:27], v[80:81], v[24:25] op_sel_hi:[0,1]
	v_pk_mul_f32 v[24:25], v[80:81], v[28:29] op_sel_hi:[0,1]
	v_mov_b32_e32 v28, v47
	v_mov_b32_e32 v29, v95
	v_mov_b32_e32 v47, v94
	v_pk_mul_f32 v[30:31], v[82:83], v[28:29] op_sel_hi:[0,1]
	v_pk_mul_f32 v[28:29], v[82:83], v[46:47] op_sel_hi:[0,1]
	v_pk_mul_f32 v[32:33], v[76:77], v[32:33] op_sel_hi:[0,1]
	v_pk_mul_f32 v[40:41], v[78:79], v[40:41] op_sel_hi:[0,1]
	v_pk_mul_f32 v[38:39], v[78:79], v[38:39] op_sel_hi:[0,1]
	v_mov_b32_e32 v56, v77
	v_mov_b32_e32 v58, v79
	v_mov_b32_e32 v52, v83
	v_pk_mul_f32 v[74:75], v[82:83], v[74:75] op_sel_hi:[0,1]
	v_pk_mul_f32 v[58:59], v[76:77], v[58:59] op_sel_hi:[0,1]
	v_pk_mul_f32 v[72:73], v[80:81], v[72:73] op_sel_hi:[0,1]
	v_pk_mul_f32 v[54:55], v[78:79], v[54:55] op_sel_hi:[0,1]
	v_pk_mul_f32 v[52:53], v[78:79], v[52:53] op_sel_hi:[0,1]
	s_andn2_b64 vcc, exec, s[20:21]
	v_pk_fma_f32 v[8:9], v[8:9], v[100:101], v[114:115]
	v_pk_fma_f32 v[10:11], v[10:11], v[102:103], v[116:117]
	v_pk_fma_f32 v[20:21], v[20:21], v[100:101], v[118:119]
	v_pk_fma_f32 v[22:23], v[22:23], v[102:103], v[120:121]
	v_pk_fma_f32 v[24:25], v[100:101], v[24:25], v[90:91]
	v_pk_fma_f32 v[26:27], v[102:103], v[26:27], v[92:93]
	v_pk_fma_f32 v[28:29], v[100:101], v[28:29], v[96:97]
	v_pk_fma_f32 v[30:31], v[102:103], v[30:31], v[98:99]
	global_store_dwordx4 v[48:49], v[8:11], off offset:-2048 sc0 sc1 nt
	global_store_dwordx4 v[50:51], v[20:23], off offset:-2048 sc0 sc1 nt
	global_store_dwordx4 v[36:37], v[24:27], off offset:-2048 sc0 sc1 nt
	global_store_dwordx4 v[70:71], v[28:31], off offset:-2048 sc0 sc1 nt
	s_nop 1
	v_mov_b32_e32 v90, v200
	v_mov_b32_e32 v91, v201
	v_mov_b32_e32 v92, v202
	v_mov_b32_e32 v93, v203
	s_nop 1
	v_mov_b32_e32 v44, v144
	v_mov_b32_e32 v45, v145
	v_mov_b32_e32 v46, v146
	v_mov_b32_e32 v47, v147
	s_nop 1
	v_mov_b32_e32 v94, v148
	v_mov_b32_e32 v95, v149
	v_mov_b32_e32 v96, v150
	v_mov_b32_e32 v97, v151
	s_nop 1
	v_mov_b32_e32 v98, v152
	v_mov_b32_e32 v99, v153
	v_mov_b32_e32 v100, v154
	v_mov_b32_e32 v101, v155
	s_nop 1
	v_mov_b32_e32 v114, v156
	v_mov_b32_e32 v115, v157
	v_mov_b32_e32 v116, v158
	v_mov_b32_e32 v117, v159
	s_nop 1
	v_mov_b32_e32 v118, v160
	v_mov_b32_e32 v119, v161
	v_mov_b32_e32 v120, v162
	v_mov_b32_e32 v121, v163
	v_pk_fma_f32 v[32:33], v[32:33], v[90:91], v[110:111]
	v_pk_fma_f32 v[34:35], v[34:35], v[92:93], v[112:113]
	v_pk_fma_f32 v[44:45], v[38:39], v[90:91], v[44:45]
	v_pk_fma_f32 v[46:47], v[40:41], v[92:93], v[46:47]
	v_pk_mul_f32 v[38:39], v[80:81], v[84:85] op_sel_hi:[0,1]
	v_pk_mul_f32 v[40:41], v[80:81], v[42:43] op_sel_hi:[0,1]
; __device__ __forceinline__ void ew_post(const bf16* Y, const float* xin, float* xout, const float* gpost, const float* gnext, bf16* H, int gw, int ngw, int lane) {
;     ...
;             for (int q = 0; q < EW_NR; ++q) { xv[q][j] = xv[q][j] + y[q][j] * rstd[q] * g; __builtin_nontemporal_store(xv[q][j], (f32x4*)(xout + (size_t)(m0 + q) * DM) + lane + 64 * j);
;                 s2[q] += (xv[q][j].x * xv[q][j].x + xv[q][j].y * xv[q][j].y) + (xv[q][j].z * xv[q][j].z + xv[q][j].w * xv[q][j].w); } }
;         if (gnext) {
;             float r2[EW_NR];
; #pragma unroll
;             for (int q = 0; q < EW_NR; ++q) r2[q] = rsqrtf(wave_sum(s2[q]) * (1.f / DM) + RMS_EPS);
	s_nop 1
	v_mov_b32_e32 v110, v164
	v_mov_b32_e32 v111, v165
	v_mov_b32_e32 v112, v166
	v_mov_b32_e32 v113, v167
	v_pk_fma_f32 v[40:41], v[40:41], v[90:91], v[94:95]
	v_pk_fma_f32 v[42:43], v[38:39], v[92:93], v[96:97]
	global_store_dwordx4 v[48:49], v[32:35], off offset:-1024 sc0 sc1 nt
	global_store_dwordx4 v[50:51], v[44:47], off offset:-1024 sc0 sc1 nt
	global_store_dwordx4 v[36:37], v[40:43], off offset:-1024 sc0 sc1 nt
	v_pk_mul_f32 v[38:39], v[82:83], v[88:89] op_sel_hi:[0,1]
	v_pk_mul_f32 v[36:37], v[82:83], v[86:87] op_sel_hi:[0,1]
	v_pk_fma_f32 v[36:37], v[90:91], v[36:37], v[98:99]
	v_pk_fma_f32 v[38:39], v[92:93], v[38:39], v[100:101]
	global_store_dwordx4 v[70:71], v[36:39], off offset:-1024 sc0 sc1 nt
	s_nop 1
	v_mov_b32_e32 v88, v204
	v_mov_b32_e32 v89, v205
	v_mov_b32_e32 v90, v206
	v_mov_b32_e32 v91, v207
	s_nop 1
	v_mov_b32_e32 v84, v168
	v_mov_b32_e32 v85, v169
	v_mov_b32_e32 v86, v170
	v_mov_b32_e32 v87, v171
	v_pk_mul_f32 v[82:83], v[82:83], v[56:57] op_sel_hi:[0,1]
	v_pk_mul_f32 v[56:57], v[76:77], v[60:61] op_sel_hi:[0,1]
	v_pk_mul_f32 v[80:81], v[80:81], v[62:63] op_sel_hi:[0,1]
	v_pk_fma_f32 v[60:61], v[58:59], v[88:89], v[114:115]
	v_pk_fma_f32 v[62:63], v[56:57], v[90:91], v[116:117]
	v_pk_fma_f32 v[56:57], v[52:53], v[88:89], v[110:111]
	v_pk_fma_f32 v[58:59], v[54:55], v[90:91], v[112:113]
	v_pk_fma_f32 v[52:53], v[80:81], v[88:89], v[118:119]
	v_pk_fma_f32 v[54:55], v[72:73], v[90:91], v[120:121]
	global_store_dwordx4 v[48:49], v[60:63], off sc0 sc1 nt
	global_store_dwordx4 v[50:51], v[56:59], off sc0 sc1 nt
	global_store_dwordx4 v[70:71], v[52:55], off offset:-4096 sc0 sc1 nt
	v_pk_fma_f32 v[48:49], v[82:83], v[88:89], v[84:85]
	v_pk_fma_f32 v[50:51], v[74:75], v[90:91], v[86:87]
	global_store_dwordx4 v[70:71], v[48:51], off sc0 sc1 nt
	s_cbranch_vccnz .LBB0_190
	v_pk_mul_f32 v[72:73], v[6:7], v[6:7]
	v_pk_mul_f32 v[74:75], v[4:5], v[4:5]
	v_mul_f32_e32 v80, v49, v49
	v_pk_mov_b32 v[76:77], v[74:75], v[72:73] op_sel:[1,0]
	v_mov_b32_e32 v75, v73
	v_pk_add_f32 v[72:73], v[76:77], v[74:75]
	v_pk_mul_f32 v[74:75], v[30:31], v[30:31]
	v_pk_mul_f32 v[76:77], v[28:29], v[28:29]
	v_mul_f32_e32 v81, v50, v50
	v_pk_mov_b32 v[78:79], v[76:77], v[74:75] op_sel:[1,0]
	v_mov_b32_e32 v77, v75
	v_pk_add_f32 v[74:75], v[78:79], v[76:77]
	v_mul_f32_e32 v76, v37, v37
	v_mul_f32_e32 v78, v48, v48
	v_pk_fma_f32 v[76:77], v[36:37], v[36:37], v[76:77] op_sel_hi:[1,1,0]
	v_mul_f32_e32 v82, v51, v51
	v_mov_b32_e32 v77, v78
	v_mul_f32_e32 v78, v39, v39
	v_pk_fma_f32 v[78:79], v[38:39], v[38:39], v[78:79] op_sel_hi:[1,1,0]
	v_pk_add_f32 v[72:73], v[72:73], v[72:73] op_sel:[0,1] op_sel_hi:[1,0]
	v_pk_add_f32 v[74:75], v[74:75], v[74:75] op_sel:[0,1] op_sel_hi:[1,0]
	v_mov_b32_e32 v79, v80
	v_mov_b32_e32 v73, v81
	v_mov_b32_e32 v75, v82
	v_pk_add_f32 v[76:77], v[76:77], v[78:79]
	v_pk_add_f32 v[72:73], v[72:73], v[74:75]
	v_pk_mul_f32 v[74:75], v[16:17], v[16:17]
	v_pk_add_f32 v[76:77], v[76:77], v[72:73]
	v_pk_mul_f32 v[72:73], v[18:19], v[18:19]
	v_mul_f32_e32 v88, v53, v53
	v_pk_mov_b32 v[78:79], v[74:75], v[72:73] op_sel:[1,0]
	v_mov_b32_e32 v75, v73
	v_pk_add_f32 v[72:73], v[78:79], v[74:75]
	v_pk_mul_f32 v[74:75], v[26:27], v[26:27]
	v_pk_mul_f32 v[78:79], v[24:25], v[24:25]
	v_mul_f32_e32 v89, v54, v54
	v_pk_mov_b32 v[80:81], v[78:79], v[74:75] op_sel:[1,0]
	v_mov_b32_e32 v79, v75
	v_pk_add_f32 v[74:75], v[80:81], v[78:79]
	v_mul_f32_e32 v80, v52, v52
	v_pk_add_f32 v[78:79], v[72:73], v[72:73] op_sel:[0,1] op_sel_hi:[1,0]
	v_pk_mul_f32 v[72:73], v[14:15], v[14:15]
	v_mov_b32_e32 v79, v80
	v_pk_mul_f32 v[80:81], v[12:13], v[12:13]
	v_mul_f32_e32 v90, v55, v55
	v_pk_mov_b32 v[82:83], v[80:81], v[72:73] op_sel:[1,0]
	v_mov_b32_e32 v81, v73
	v_pk_add_f32 v[72:73], v[82:83], v[80:81]
	v_pk_mul_f32 v[80:81], v[22:23], v[22:23]
	v_pk_mul_f32 v[82:83], v[20:21], v[20:21]
	v_pk_add_f32 v[72:73], v[72:73], v[72:73] op_sel:[0,1] op_sel_hi:[1,0]
	v_pk_mov_b32 v[84:85], v[82:83], v[80:81] op_sel:[1,0]
	v_mov_b32_e32 v83, v81
	v_pk_add_f32 v[80:81], v[84:85], v[82:83]
	v_mul_f32_e32 v82, v56, v56
	v_mul_f32_e32 v83, v57, v57
	v_pk_add_f32 v[80:81], v[80:81], v[80:81] op_sel:[0,1] op_sel_hi:[1,0]
	v_mov_b32_e32 v73, v82
	v_mov_b32_e32 v81, v83
	v_pk_add_f32 v[72:73], v[72:73], v[80:81]
	v_mul_f32_e32 v80, v45, v45
	v_mul_f32_e32 v82, v47, v47
	v_mul_f32_e32 v84, v58, v58
	v_mul_f32_e32 v85, v59, v59
	v_pk_fma_f32 v[80:81], v[44:45], v[44:45], v[80:81] op_sel_hi:[1,1,0]
	v_pk_fma_f32 v[82:83], v[46:47], v[46:47], v[82:83] op_sel_hi:[1,1,0]
	v_mov_b32_e32 v81, v84
	v_mov_b32_e32 v83, v85
	v_pk_add_f32 v[80:81], v[80:81], v[82:83]
	v_pk_mul_f32 v[82:83], v[0:1], v[0:1]
	v_pk_add_f32 v[72:73], v[72:73], v[80:81]
	v_pk_mul_f32 v[80:81], v[2:3], v[2:3]
	s_nop 0
	v_pk_mov_b32 v[84:85], v[82:83], v[80:81] op_sel:[1,0]
	v_mov_b32_e32 v83, v81
	v_pk_add_f32 v[80:81], v[84:85], v[82:83]
	v_pk_mul_f32 v[82:83], v[10:11], v[10:11]
	v_pk_mul_f32 v[84:85], v[8:9], v[8:9]
	v_pk_add_f32 v[80:81], v[80:81], v[80:81] op_sel:[0,1] op_sel_hi:[1,0]
	v_pk_mov_b32 v[86:87], v[84:85], v[82:83] op_sel:[1,0]
	v_mov_b32_e32 v85, v83
	v_pk_add_f32 v[82:83], v[86:87], v[84:85]
	v_mul_f32_e32 v84, v60, v60
	v_mul_f32_e32 v85, v61, v61
	v_pk_add_f32 v[82:83], v[82:83], v[82:83] op_sel:[0,1] op_sel_hi:[1,0]
	v_mov_b32_e32 v81, v84
	v_mov_b32_e32 v83, v85
	v_pk_add_f32 v[80:81], v[80:81], v[82:83]
	v_mul_f32_e32 v82, v33, v33
	v_mul_f32_e32 v84, v35, v35
	v_mul_f32_e32 v86, v62, v62
	v_mul_f32_e32 v87, v63, v63
	v_pk_fma_f32 v[82:83], v[32:33], v[32:33], v[82:83] op_sel_hi:[1,1,0]
	v_pk_fma_f32 v[84:85], v[34:35], v[34:35], v[84:85] op_sel_hi:[1,1,0]
	v_mov_b32_e32 v83, v86
	v_mov_b32_e32 v85, v87
	v_pk_add_f32 v[82:83], v[82:83], v[84:85]
	v_pk_add_f32 v[84:85], v[74:75], v[74:75] op_sel:[0,1] op_sel_hi:[1,0]
	v_pk_add_f32 v[80:81], v[80:81], v[82:83]
	v_mov_b32_e32 v82, v72
	v_mov_b32_e32 v83, v80
	v_mov_b32_e32 v80, v73
	s_nop 1
	v_mov_b32_e32 v72, v208
	v_mov_b32_e32 v73, v209
	v_mov_b32_e32 v74, v210
	v_mov_b32_e32 v75, v211
	v_pk_add_f32 v[80:81], v[82:83], v[80:81]
	v_mov_b32_e32 v85, v88
	ds_bpermute_b32 v83, v104, v81
	ds_bpermute_b32 v82, v104, v80
	v_pk_add_f32 v[78:79], v[78:79], v[84:85]
	v_mul_f32_e32 v84, v41, v41
	v_mul_f32_e32 v86, v43, v43
	v_pk_fma_f32 v[84:85], v[40:41], v[40:41], v[84:85] op_sel_hi:[1,1,0]
	v_pk_fma_f32 v[86:87], v[42:43], v[42:43], v[86:87] op_sel_hi:[1,1,0]
	v_mov_b32_e32 v85, v89
	v_mov_b32_e32 v87, v90
	v_pk_add_f32 v[84:85], v[84:85], v[86:87]
	s_waitcnt lgkmcnt(0)
; __device__ __forceinline__ void ew_post(const bf16* Y, const float* xin, float* xout, const float* gpost, const float* gnext, bf16* H, int gw, int ngw, int lane) {
;     ...
;             for (int q = 0; q < EW_NR; ++q) r2[q] = rsqrtf(wave_sum(s2[q]) * (1.f / DM) + RMS_EPS);
	v_pk_add_f32 v[80:81], v[80:81], v[82:83]
	v_pk_add_f32 v[78:79], v[78:79], v[84:85]
	v_mov_b32_e32 v84, v76
	v_mov_b32_e32 v85, v78
	v_mov_b32_e32 v78, v77
	ds_bpermute_b32 v83, v105, v81
	ds_bpermute_b32 v82, v105, v80
	v_pk_add_f32 v[76:77], v[84:85], v[78:79]
	ds_bpermute_b32 v79, v104, v77
	ds_bpermute_b32 v78, v104, v76
	s_waitcnt lgkmcnt(2)
	v_pk_add_f32 v[80:81], v[80:81], v[82:83]
	ds_bpermute_b32 v83, v106, v81
	ds_bpermute_b32 v82, v106, v80
	s_waitcnt lgkmcnt(2)
	v_pk_add_f32 v[76:77], v[76:77], v[78:79]
	ds_bpermute_b32 v79, v105, v77
	ds_bpermute_b32 v78, v105, v76
	s_waitcnt lgkmcnt(2)
	v_pk_add_f32 v[80:81], v[80:81], v[82:83]
	ds_bpermute_b32 v83, v107, v81
	ds_bpermute_b32 v82, v107, v80
	s_waitcnt lgkmcnt(2)
	v_pk_add_f32 v[76:77], v[76:77], v[78:79]
	ds_bpermute_b32 v79, v106, v77
	ds_bpermute_b32 v78, v106, v76
	s_waitcnt lgkmcnt(2)
	v_pk_add_f32 v[80:81], v[80:81], v[82:83]
	ds_bpermute_b32 v83, v108, v81
	ds_bpermute_b32 v82, v108, v80
	s_waitcnt lgkmcnt(2)
	v_pk_add_f32 v[76:77], v[76:77], v[78:79]
	ds_bpermute_b32 v79, v107, v77
	ds_bpermute_b32 v78, v107, v76
	s_waitcnt lgkmcnt(2)
	v_pk_add_f32 v[80:81], v[80:81], v[82:83]
	ds_bpermute_b32 v83, v109, v81
	ds_bpermute_b32 v82, v109, v80
	s_waitcnt lgkmcnt(2)
	v_pk_add_f32 v[76:77], v[76:77], v[78:79]
	ds_bpermute_b32 v79, v108, v77
	ds_bpermute_b32 v78, v108, v76
	s_waitcnt lgkmcnt(2)
	v_pk_add_f32 v[80:81], v[80:81], v[82:83]
	v_mov_b64_e32 v[82:83], s[24:25]
	v_pk_fma_f32 v[80:81], v[80:81], s[44:45], v[82:83] op_sel_hi:[1,0,0]
	s_waitcnt lgkmcnt(0)
	v_pk_add_f32 v[76:77], v[76:77], v[78:79]
	v_mul_f32_e32 v84, 0x4b800000, v81
	v_cmp_gt_f32_e32 vcc, s3, v81
	ds_bpermute_b32 v79, v109, v77
	ds_bpermute_b32 v78, v109, v76
	v_cndmask_b32_e32 v81, v81, v84, vcc
	v_rsq_f32_e32 v81, v81
	v_mul_f32_e32 v84, 0x4b800000, v80
	v_cmp_gt_f32_e64 s[4:5], s3, v80
	s_waitcnt lgkmcnt(0)
; __device__ __forceinline__ unsigned pk2(float lo, float hi) { f32v2 v = {lo, hi}; bf16v2 r = __builtin_convertvector(v, bf16v2); return __builtin_bit_cast(unsigned, r); }
; __device__ __forceinline__ void ew_post(const bf16* Y, const float* xin, float* xout, const float* gpost, const float* gnext, bf16* H, int gw, int ngw, int lane) {
;     ...
;             for (int q = 0; q < EW_NR; ++q) r2[q] = rsqrtf(wave_sum(s2[q]) * (1.f / DM) + RMS_EPS);
; #pragma unroll
;             for (int j = 0; j < 4; ++j) { const f32x4 g = *((const f32x4*)gnext + lane + 64 * j);
; #pragma unroll
;                 for (int q = 0; q < EW_NR; ++q) { v2u w; w.x = pk2(xv[q][j].x * r2[q] * g.x, xv[q][j].y * r2[q] * g.y); w.y = pk2(xv[q][j].z * r2[q] * g.z, xv[q][j].w * r2[q] * g.w);
;                     *((v2u*)(H + (size_t)(m0 + q) * DM) + lane + 64 * j) = w; } }
	v_pk_add_f32 v[76:77], v[76:77], v[78:79]
	v_cndmask_b32_e64 v80, v80, v84, s[4:5]
	v_rsq_f32_e32 v84, v80
	v_mul_f32_e32 v80, 0x45800000, v81
	v_pk_fma_f32 v[76:77], v[76:77], s[44:45], v[82:83] op_sel_hi:[1,0,0]
	v_cndmask_b32_e32 v80, v81, v80, vcc
	v_mul_f32_e32 v78, 0x4b800000, v77
	v_cmp_gt_f32_e32 vcc, s3, v77
	v_cmp_gt_f32_e64 s[6:7], s3, v76
	v_mul_f32_e32 v81, 0x45800000, v84
	v_cndmask_b32_e32 v77, v77, v78, vcc
	v_rsq_f32_e32 v77, v77
	v_mul_f32_e32 v78, 0x4b800000, v76
	v_cndmask_b32_e64 v76, v76, v78, s[6:7]
	v_rsq_f32_e32 v79, v76
	v_mul_f32_e32 v78, 0x45800000, v77
	v_pk_mul_f32 v[0:1], v[0:1], v[80:81] op_sel_hi:[1,0]
	v_pk_mul_f32 v[2:3], v[2:3], v[80:81] op_sel_hi:[1,0]
	v_cndmask_b32_e64 v76, v84, v81, s[4:5]
	v_cndmask_b32_e32 v78, v77, v78, vcc
	v_pk_mul_f32 v[0:1], v[0:1], v[72:73]
	v_pk_mul_f32 v[2:3], v[2:3], v[74:75]
	v_add_co_u32_e32 v84, vcc, s22, v68
	v_mul_f32_e32 v77, 0x45800000, v79
	v_cvt_pk_bf16_f32 v0, v0, v1
	v_cvt_pk_bf16_f32 v1, v2, v3
	v_addc_co_u32_e32 v85, vcc, -1, v69, vcc
	global_store_dwordx2 v[84:85], v[0:1], off offset:-3584
	v_pk_mul_f32 v[0:1], v[12:13], v[76:77] op_sel_hi:[1,0]
	v_pk_mul_f32 v[2:3], v[14:15], v[76:77] op_sel_hi:[1,0]
	v_pk_mul_f32 v[0:1], v[0:1], v[72:73]
	v_pk_mul_f32 v[2:3], v[2:3], v[74:75]
	v_cvt_pk_bf16_f32 v0, v0, v1
	v_cvt_pk_bf16_f32 v1, v2, v3
	global_store_dwordx2 v[84:85], v[0:1], off offset:-1536
	v_pk_mul_f32 v[0:1], v[16:17], v[78:79] op_sel_hi:[1,0]
	v_pk_mul_f32 v[2:3], v[18:19], v[78:79] op_sel_hi:[1,0]
	v_pk_mul_f32 v[0:1], v[72:73], v[0:1]
	v_pk_mul_f32 v[2:3], v[74:75], v[2:3]
	v_add_co_u32_e32 v12, vcc, s23, v68
	v_cndmask_b32_e64 v82, v79, v77, s[6:7]
	v_cvt_pk_bf16_f32 v0, v0, v1
	v_cvt_pk_bf16_f32 v1, v2, v3
	v_addc_co_u32_e32 v13, vcc, -1, v69, vcc
	global_store_dwordx2 v[12:13], v[0:1], off offset:-3584
	v_pk_mul_f32 v[0:1], v[4:5], v[82:83] op_sel_hi:[1,0]
	v_pk_mul_f32 v[2:3], v[6:7], v[82:83] op_sel_hi:[1,0]
	v_pk_mul_f32 v[0:1], v[72:73], v[0:1]
	v_pk_mul_f32 v[2:3], v[74:75], v[2:3]
	v_cvt_pk_bf16_f32 v0, v0, v1
	v_cvt_pk_bf16_f32 v1, v2, v3
	global_store_dwordx2 v[12:13], v[0:1], off offset:-1536
	s_nop 1
	v_mov_b32_e32 v0, v212
	v_mov_b32_e32 v1, v213
	v_mov_b32_e32 v2, v214
	v_mov_b32_e32 v3, v215
	v_pk_mul_f32 v[4:5], v[8:9], v[80:81] op_sel_hi:[1,0]
	v_pk_mul_f32 v[6:7], v[10:11], v[80:81] op_sel_hi:[1,0]
	v_pk_mul_f32 v[8:9], v[56:57], v[76:77] op_sel_hi:[1,0]
	v_pk_mul_f32 v[10:11], v[58:59], v[76:77] op_sel_hi:[1,0]
	v_pk_mul_f32 v[14:15], v[52:53], v[78:79] op_sel_hi:[1,0]
	v_pk_mul_f32 v[16:17], v[54:55], v[78:79] op_sel_hi:[1,0]
	v_pk_mul_f32 v[18:19], v[48:49], v[82:83] op_sel_hi:[1,0]
	v_pk_mul_f32 v[4:5], v[4:5], v[0:1]
	v_pk_mul_f32 v[6:7], v[6:7], v[2:3]
	v_cvt_pk_bf16_f32 v4, v4, v5
	v_cvt_pk_bf16_f32 v5, v6, v7
	global_store_dwordx2 v[84:85], v[4:5], off offset:-3072
	v_pk_mul_f32 v[4:5], v[20:21], v[76:77] op_sel_hi:[1,0]
	v_pk_mul_f32 v[6:7], v[22:23], v[76:77] op_sel_hi:[1,0]
	v_pk_mul_f32 v[4:5], v[4:5], v[0:1]
	v_pk_mul_f32 v[6:7], v[6:7], v[2:3]
	v_cvt_pk_bf16_f32 v4, v4, v5
	v_cvt_pk_bf16_f32 v5, v6, v7
	global_store_dwordx2 v[84:85], v[4:5], off offset:-1024
	v_pk_mul_f32 v[4:5], v[24:25], v[78:79] op_sel_hi:[1,0]
	v_pk_mul_f32 v[6:7], v[26:27], v[78:79] op_sel_hi:[1,0]
	v_pk_mul_f32 v[4:5], v[4:5], v[0:1]
	v_pk_mul_f32 v[6:7], v[6:7], v[2:3]
	v_cvt_pk_bf16_f32 v4, v4, v5
	v_cvt_pk_bf16_f32 v5, v6, v7
	global_store_dwordx2 v[12:13], v[4:5], off offset:-3072
	v_pk_mul_f32 v[4:5], v[28:29], v[82:83] op_sel_hi:[1,0]
	v_pk_mul_f32 v[6:7], v[34:35], v[80:81] op_sel_hi:[1,0]
	v_pk_mul_f32 v[0:1], v[0:1], v[4:5]
	v_pk_mul_f32 v[4:5], v[30:31], v[82:83] op_sel_hi:[1,0]
	v_cvt_pk_bf16_f32 v0, v0, v1
	v_pk_mul_f32 v[2:3], v[2:3], v[4:5]
	v_pk_mul_f32 v[4:5], v[32:33], v[80:81] op_sel_hi:[1,0]
	v_cvt_pk_bf16_f32 v1, v2, v3
	global_store_dwordx2 v[12:13], v[0:1], off offset:-1024
	s_nop 1
	v_mov_b32_e32 v0, v216
	v_mov_b32_e32 v1, v217
	v_mov_b32_e32 v2, v218
	v_mov_b32_e32 v3, v219
	v_pk_mul_f32 v[20:21], v[50:51], v[82:83] op_sel_hi:[1,0]
	v_pk_mul_f32 v[4:5], v[4:5], v[0:1]
	v_pk_mul_f32 v[6:7], v[6:7], v[2:3]
	v_cvt_pk_bf16_f32 v4, v4, v5
	v_cvt_pk_bf16_f32 v5, v6, v7
	global_store_dwordx2 v[84:85], v[4:5], off offset:-2560
	v_pk_mul_f32 v[4:5], v[44:45], v[76:77] op_sel_hi:[1,0]
	v_pk_mul_f32 v[6:7], v[46:47], v[76:77] op_sel_hi:[1,0]
	v_pk_mul_f32 v[4:5], v[4:5], v[0:1]
	v_pk_mul_f32 v[6:7], v[6:7], v[2:3]
	v_cvt_pk_bf16_f32 v4, v4, v5
	v_cvt_pk_bf16_f32 v5, v6, v7
	global_store_dwordx2 v[84:85], v[4:5], off offset:-512
	v_pk_mul_f32 v[4:5], v[40:41], v[78:79] op_sel_hi:[1,0]
	v_pk_mul_f32 v[6:7], v[42:43], v[78:79] op_sel_hi:[1,0]
	v_pk_mul_f32 v[4:5], v[4:5], v[0:1]
	v_pk_mul_f32 v[6:7], v[6:7], v[2:3]
	v_cvt_pk_bf16_f32 v4, v4, v5
	v_cvt_pk_bf16_f32 v5, v6, v7
	global_store_dwordx2 v[12:13], v[4:5], off offset:-2560
	v_pk_mul_f32 v[4:5], v[36:37], v[82:83] op_sel_hi:[1,0]
	v_pk_mul_f32 v[6:7], v[62:63], v[80:81] op_sel_hi:[1,0]
	v_pk_mul_f32 v[0:1], v[4:5], v[0:1]
	v_pk_mul_f32 v[4:5], v[38:39], v[82:83] op_sel_hi:[1,0]
	v_cvt_pk_bf16_f32 v0, v0, v1
	v_pk_mul_f32 v[2:3], v[4:5], v[2:3]
	v_pk_mul_f32 v[4:5], v[60:61], v[80:81] op_sel_hi:[1,0]
	v_cvt_pk_bf16_f32 v1, v2, v3
	global_store_dwordx2 v[12:13], v[0:1], off offset:-512
	s_nop 1
	v_mov_b32_e32 v0, v220
	v_mov_b32_e32 v1, v221
	v_mov_b32_e32 v2, v222
	v_mov_b32_e32 v3, v223
	v_pk_mul_f32 v[4:5], v[4:5], v[0:1]
	v_pk_mul_f32 v[6:7], v[6:7], v[2:3]
	v_pk_mul_f32 v[8:9], v[8:9], v[0:1]
	v_pk_mul_f32 v[10:11], v[10:11], v[2:3]
	v_pk_mul_f32 v[14:15], v[14:15], v[0:1]
	v_pk_mul_f32 v[16:17], v[16:17], v[2:3]
	v_pk_mul_f32 v[0:1], v[18:19], v[0:1]
	v_pk_mul_f32 v[2:3], v[20:21], v[2:3]
	v_cvt_pk_bf16_f32 v4, v4, v5
	v_cvt_pk_bf16_f32 v5, v6, v7
	v_cvt_pk_bf16_f32 v6, v8, v9
	v_cvt_pk_bf16_f32 v7, v10, v11
	v_cvt_pk_bf16_f32 v8, v14, v15
	v_cvt_pk_bf16_f32 v9, v16, v17
	v_cvt_pk_bf16_f32 v0, v0, v1
	v_cvt_pk_bf16_f32 v1, v2, v3
	global_store_dwordx2 v[84:85], v[4:5], off offset:-2048
	global_store_dwordx2 v[12:13], v[6:7], off offset:-4096
	global_store_dwordx2 v[12:13], v[8:9], off offset:-2048
	global_store_dwordx2 v[12:13], v[0:1], off
	s_branch .LBB0_190

; __device__ __forceinline__ void ew_post(const bf16* Y, const float* xin, float* xout, const float* gpost, const float* gnext, bf16* H, int gw, int ngw, int lane) {
;     for (int m0 = EW_NR * gw; m0 < NTOK; m0 += EW_NR * ngw) {
;         f32x4 y[EW_NR][4], xv[EW_NR][4]; float s[EW_NR];
; #pragma unroll
;         for (int q = 0; q < EW_NR; ++q) { const v2u* yr = (const v2u*)(Y + (size_t)(m0 + q) * DM) + lane; const f32x4* xr = (const f32x4*)(xin + (size_t)(m0 + q) * DM) + lane;
; #pragma unroll
;             for (int j = 0; j < 4; ++j) { const v2u w = __builtin_nontemporal_load(yr + 64 * j); y[q][j] = (f32x4){bf_lo(w.x), bf_hi(w.x), bf_lo(w.y), bf_hi(w.y)}; xv[q][j] = __builtin_nontemporal_load(xr + 64 * j); } }
.LBB0_209:
	v_add_co_u32_e32 v8, vcc, 0xfffff000, v72
	global_load_dwordx2 v[38:39], v[72:73], off offset:-4096 nt
	global_load_dwordx2 v[40:41], v[72:73], off offset:-2048 nt
	v_addc_co_u32_e32 v9, vcc, -1, v73, vcc
	global_load_dwordx2 v[42:43], v[72:73], off nt
	global_load_dwordx2 v[48:49], v[8:9], off offset:-2048 nt
	global_load_dwordx2 v[50:51], v[8:9], off offset:-3584 nt
	global_load_dwordx2 v[52:53], v[8:9], off offset:-3072 nt
	global_load_dwordx2 v[54:55], v[8:9], off offset:-2560 nt
	v_lshl_add_u64 v[10:11], s[12:13], 0, v[178:179]
	global_load_dwordx2 v[96:97], v[72:73], off offset:-3584 nt
	global_load_dwordx2 v[106:107], v[72:73], off offset:-3072 nt
	global_load_dwordx2 v[98:99], v[72:73], off offset:-2560 nt
	global_load_dwordx2 v[108:109], v[72:73], off offset:-1536 nt
	global_load_dwordx2 v[66:67], v[72:73], off offset:-1024 nt
	global_load_dwordx2 v[46:47], v[72:73], off offset:-512 nt
	global_load_dwordx2 v[90:91], v[8:9], off offset:-1536 nt
	global_load_dwordx4 v[20:23], v[10:11], off nt
	global_load_dwordx4 v[12:15], v[10:11], off offset:1024 nt
	global_load_dwordx4 v[4:7], v[10:11], off offset:2048 nt
	global_load_dwordx4 v[0:3], v[10:11], off offset:3072 nt
	global_load_dwordx2 v[92:93], v[8:9], off offset:-1024 nt
	global_load_dwordx2 v[104:105], v[8:9], off offset:-512 nt
	v_add_co_u32_e64 v36, s[4:5], s24, v10
	v_add_co_u32_e32 v44, vcc, s22, v10
	s_nop 0
	v_addc_co_u32_e64 v37, s[4:5], 0, v11, s[4:5]
	s_mov_b64 s[4:5], vcc
	v_add_co_u32_e32 v64, vcc, s23, v10
	v_addc_co_u32_e64 v45, s[4:5], 0, v11, s[4:5]
	global_load_dwordx4 v[28:31], v[36:37], off nt
	v_addc_co_u32_e32 v65, vcc, 0, v11, vcc
	global_load_dwordx4 v[16:19], v[44:45], off offset:1024 nt
	global_load_dwordx4 v[8:11], v[44:45], off offset:2048 nt
	global_load_dwordx4 v[24:27], v[64:65], off offset:-4096 nt
	global_load_dwordx4 v[32:35], v[64:65], off nt
	s_nop 1
	v_mov_b32_e32 v136, v156
	v_mov_b32_e32 v137, v157
	v_mov_b32_e32 v138, v158
	v_mov_b32_e32 v139, v159
	v_mov_b64_e32 v[148:149], s[26:27]
	global_load_dwordx4 v[192:195], v[44:45], off offset:3072 nt
	global_load_dwordx4 v[196:199], v[64:65], off offset:1024 nt
	global_load_dwordx4 v[200:203], v[64:65], off offset:2048 nt
	global_load_dwordx4 v[204:207], v[64:65], off offset:3072 nt
	global_load_dwordx4 v[208:211], v[36:37], off offset:1024 nt
	global_load_dwordx4 v[212:215], v[36:37], off offset:2048 nt
	global_load_dwordx4 v[216:219], v[36:37], off offset:3072 nt
	s_waitcnt vmcnt(7)
	v_and_b32_e32 v121, 0xffff0000, v97
	v_and_b32_e32 v119, 0xffff0000, v96
	v_lshlrev_b32_e32 v120, 16, v97
	v_lshlrev_b32_e32 v118, 16, v96
	v_lshlrev_b32_e32 v59, 16, v38
	v_lshlrev_b32_e32 v77, 16, v40
	v_lshlrev_b32_e32 v87, 16, v48
	v_and_b32_e32 v101, 0xffff0000, v50
	v_and_b32_e32 v103, 0xffff0000, v51
	v_and_b32_e32 v75, 0xffff0000, v40
	v_lshlrev_b32_e32 v78, 16, v41
	v_and_b32_e32 v79, 0xffff0000, v41
	v_lshlrev_b32_e32 v83, 16, v42
	v_and_b32_e32 v81, 0xffff0000, v42
	v_lshlrev_b32_e32 v84, 16, v43
	v_and_b32_e32 v85, 0xffff0000, v43
	v_and_b32_e32 v63, 0xffff0000, v48
	v_lshlrev_b32_e32 v88, 16, v49
	v_and_b32_e32 v89, 0xffff0000, v49
	v_lshlrev_b32_e32 v100, 16, v50
	v_lshlrev_b32_e32 v102, 16, v51
	v_and_b32_e32 v41, 0xffff0000, v53
	v_and_b32_e32 v40, 0xffff0000, v52
	v_lshlrev_b32_e32 v48, 16, v54
	v_and_b32_e32 v49, 0xffff0000, v54
	v_mul_f32_e32 v42, v103, v103
	v_mul_f32_e32 v54, v101, v101
	v_mov_b32_e32 v43, v87
	v_and_b32_e32 v57, 0xffff0000, v38
	v_lshlrev_b32_e32 v60, 16, v39
	v_and_b32_e32 v61, 0xffff0000, v39
	v_lshlrev_b32_e32 v39, 16, v53
	v_lshlrev_b32_e32 v38, 16, v52
	v_lshlrev_b32_e32 v50, 16, v55
	v_and_b32_e32 v51, 0xffff0000, v55
	v_pk_mul_f32 v[52:53], v[40:41], v[40:41]
	v_pk_fma_f32 v[94:95], v[102:103], v[102:103], v[42:43] op_sel_hi:[1,1,0]
	v_pk_fma_f32 v[54:55], v[100:101], v[100:101], v[54:55] op_sel_hi:[1,1,0]
	v_pk_fma_f32 v[52:53], v[38:39], v[38:39], v[52:53]
	v_mov_b32_e32 v86, v54
	v_mov_b32_e32 v42, v94
	v_mul_f32_e32 v56, v63, v63
	v_pk_add_f32 v[54:55], v[54:55], v[94:95]
	v_pk_add_f32 v[52:53], v[52:53], v[52:53] op_sel:[0,1] op_sel_hi:[1,0]
	v_pk_mul_f32 v[42:43], v[86:87], v[42:43]
	v_mov_b32_e32 v53, v56
	v_mov_b32_e32 v55, v43
	v_pk_add_f32 v[42:43], v[54:55], v[52:53]
	v_mul_f32_e32 v52, v49, v49
	v_mul_f32_e32 v54, v51, v51
	v_mul_f32_e32 v58, v88, v88
	v_mul_f32_e32 v62, v89, v89
	v_pk_fma_f32 v[52:53], v[48:49], v[48:49], v[52:53] op_sel_hi:[1,1,0]
	v_pk_fma_f32 v[54:55], v[50:51], v[50:51], v[54:55] op_sel_hi:[1,1,0]
	v_mov_b32_e32 v53, v58
	v_mov_b32_e32 v55, v62
	v_pk_add_f32 v[52:53], v[52:53], v[54:55]
	v_and_b32_e32 v113, 0xffff0000, v91
	v_pk_add_f32 v[52:53], v[42:43], v[52:53]
	v_and_b32_e32 v111, 0xffff0000, v90
	v_lshlrev_b32_e32 v112, 16, v91
	v_mul_f32_e32 v42, v113, v113
	v_and_b32_e32 v95, 0xffff0000, v93
	v_and_b32_e32 v94, 0xffff0000, v92
	v_lshlrev_b32_e32 v110, 16, v90
	v_pk_fma_f32 v[54:55], v[112:113], v[112:113], v[42:43] op_sel_hi:[1,1,0]
	v_lshlrev_b32_e32 v43, 16, v93
	v_lshlrev_b32_e32 v42, 16, v92
	v_pk_mul_f32 v[90:91], v[94:95], v[94:95]
	v_mul_f32_e32 v56, v111, v111
	v_pk_fma_f32 v[114:115], v[42:43], v[42:43], v[90:91]
	v_lshlrev_b32_e32 v90, 16, v104
	v_and_b32_e32 v91, 0xffff0000, v104
	v_lshlrev_b32_e32 v92, 16, v105
	v_and_b32_e32 v93, 0xffff0000, v105
	v_pk_fma_f32 v[104:105], v[110:111], v[110:111], v[56:57] op_sel_hi:[1,1,0]
	v_mov_b32_e32 v116, v54
	v_mov_b32_e32 v58, v104
	v_mov_b32_e32 v117, v59
	v_pk_add_f32 v[54:55], v[104:105], v[54:55]
	v_pk_mul_f32 v[104:105], v[58:59], v[116:117]
	v_mul_f32_e32 v62, v57, v57
	v_mov_b32_e32 v55, v105
	v_pk_add_f32 v[104:105], v[114:115], v[114:115] op_sel:[0,1] op_sel_hi:[1,0]
	v_mul_f32_e32 v56, v91, v91
	v_mov_b32_e32 v105, v62
	v_pk_add_f32 v[54:55], v[54:55], v[104:105]
	v_pk_fma_f32 v[104:105], v[90:91], v[90:91], v[56:57] op_sel_hi:[1,1,0]
	v_mul_f32_e32 v56, v93, v93
	v_mul_f32_e32 v74, v60, v60
	v_mul_f32_e32 v76, v61, v61
	v_pk_fma_f32 v[114:115], v[92:93], v[92:93], v[56:57] op_sel_hi:[1,1,0]
	v_mov_b32_e32 v105, v74
	v_mov_b32_e32 v115, v76
	v_pk_add_f32 v[104:105], v[104:105], v[114:115]
	v_mov_b32_e32 v143, v52
	v_pk_add_f32 v[54:55], v[54:55], v[104:105]
	v_mul_f32_e32 v56, v121, v121
	v_mov_b32_e32 v142, v54
	v_mov_b32_e32 v52, v55
	v_pk_add_f32 v[52:53], v[142:143], v[52:53]
	ds_bpermute_b32 v55, v130, v53
	ds_bpermute_b32 v54, v130, v52
	v_pk_fma_f32 v[114:115], v[120:121], v[120:121], v[56:57] op_sel_hi:[1,1,0]
	v_lshlrev_b32_e32 v105, 16, v107
	v_lshlrev_b32_e32 v104, 16, v106
	v_and_b32_e32 v107, 0xffff0000, v107
	v_and_b32_e32 v106, 0xffff0000, v106
	v_mul_f32_e32 v56, v119, v119
	v_pk_mul_f32 v[96:97], v[106:107], v[106:107]
	v_pk_fma_f32 v[122:123], v[118:119], v[118:119], v[56:57] op_sel_hi:[1,1,0]
	s_waitcnt lgkmcnt(0)
; __device__ __forceinline__ void ew_post(const bf16* Y, const float* xin, float* xout, const float* gpost, const float* gnext, bf16* H, int gw, int ngw, int lane) {
;     ...
;         for (int q = 0; q < EW_NR; ++q) { s[q] = 0.f;
; #pragma unroll
;             for (int j = 0; j < 4; ++j) s[q] += (y[q][j].x * y[q][j].x + y[q][j].y * y[q][j].y) + (y[q][j].z * y[q][j].z + y[q][j].w * y[q][j].w); }
;         float rstd[EW_NR], s2[EW_NR];
; #pragma unroll
;         for (int q = 0; q < EW_NR; ++q) { rstd[q] = rsqrtf(wave_sum(s[q]) * (1.f / DM) + RMS_EPS); s2[q] = 0.f; }
; #pragma unroll
;         for (int j = 0; j < 4; ++j) { const f32x4 g = *((const f32x4*)gpost + lane + 64 * j);
; #pragma unroll
;             for (int q = 0; q < EW_NR; ++q) { xv[q][j] = xv[q][j] + y[q][j] * rstd[q] * g; __builtin_nontemporal_store(xv[q][j], (f32x4*)(xout + (size_t)(m0 + q) * DM) + lane + 64 * j);
	v_pk_add_f32 v[52:53], v[52:53], v[54:55]
	v_pk_fma_f32 v[116:117], v[104:105], v[104:105], v[96:97]
	v_mov_b32_e32 v76, v122
	v_mov_b32_e32 v124, v114
	v_mov_b32_e32 v125, v77
	ds_bpermute_b32 v55, v131, v53
	ds_bpermute_b32 v54, v131, v52
	v_and_b32_e32 v97, 0xffff0000, v98
	v_mul_f32_e32 v58, v75, v75
	v_pk_add_f32 v[114:115], v[122:123], v[114:115]
	v_pk_mul_f32 v[122:123], v[76:77], v[124:125]
	v_pk_add_f32 v[116:117], v[116:117], v[116:117] op_sel:[0,1] op_sel_hi:[1,0]
	v_lshlrev_b32_e32 v96, 16, v98
	v_lshlrev_b32_e32 v98, 16, v99
	v_and_b32_e32 v99, 0xffff0000, v99
	v_mov_b32_e32 v115, v123
	v_mov_b32_e32 v117, v58
	v_mul_f32_e32 v56, v97, v97
	v_pk_add_f32 v[114:115], v[114:115], v[116:117]
	v_pk_fma_f32 v[116:117], v[96:97], v[96:97], v[56:57] op_sel_hi:[1,1,0]
	v_mul_f32_e32 v56, v99, v99
	v_mul_f32_e32 v62, v78, v78
	v_mul_f32_e32 v74, v79, v79
	v_pk_fma_f32 v[122:123], v[98:99], v[98:99], v[56:57] op_sel_hi:[1,1,0]
	v_mov_b32_e32 v117, v62
	v_mov_b32_e32 v123, v74
	s_waitcnt lgkmcnt(0)
	v_pk_add_f32 v[52:53], v[52:53], v[54:55]
	v_pk_add_f32 v[116:117], v[116:117], v[122:123]
	v_and_b32_e32 v123, 0xffff0000, v108
	v_and_b32_e32 v125, 0xffff0000, v109
	ds_bpermute_b32 v55, v132, v53
	ds_bpermute_b32 v54, v132, v52
	v_pk_add_f32 v[128:129], v[114:115], v[116:117]
	v_lshlrev_b32_e32 v122, 16, v108
	v_lshlrev_b32_e32 v124, 16, v109
	v_mul_f32_e32 v56, v125, v125
	v_and_b32_e32 v117, 0xffff0000, v67
	v_and_b32_e32 v116, 0xffff0000, v66
	v_lshlrev_b32_e32 v108, 16, v46
	v_and_b32_e32 v109, 0xffff0000, v46
	v_mul_f32_e32 v46, v123, v123
	v_pk_fma_f32 v[140:141], v[124:125], v[124:125], v[56:57] op_sel_hi:[1,1,0]
	v_lshlrev_b32_e32 v115, 16, v67
	v_lshlrev_b32_e32 v114, 16, v66
	v_pk_mul_f32 v[66:67], v[116:117], v[116:117]
	v_lshlrev_b32_e32 v126, 16, v47
	v_and_b32_e32 v127, 0xffff0000, v47
	v_pk_fma_f32 v[46:47], v[122:123], v[122:123], v[46:47] op_sel_hi:[1,1,0]
	v_pk_fma_f32 v[66:67], v[114:115], v[114:115], v[66:67]
	v_mov_b32_e32 v82, v46
	v_mov_b32_e32 v142, v140
	v_mov_b32_e32 v143, v83
	v_mul_f32_e32 v56, v81, v81
	v_pk_add_f32 v[46:47], v[46:47], v[140:141]
	v_pk_mul_f32 v[140:141], v[82:83], v[142:143]
	v_pk_add_f32 v[66:67], v[66:67], v[66:67] op_sel:[0,1] op_sel_hi:[1,0]
	v_mov_b32_e32 v47, v141
	v_mov_b32_e32 v67, v56
	v_mul_f32_e32 v56, v109, v109
	s_waitcnt lgkmcnt(0)
	v_pk_add_f32 v[52:53], v[52:53], v[54:55]
	v_pk_add_f32 v[46:47], v[46:47], v[66:67]
	v_pk_fma_f32 v[66:67], v[108:109], v[108:109], v[56:57] op_sel_hi:[1,1,0]
	v_mul_f32_e32 v56, v127, v127
	ds_bpermute_b32 v55, v133, v53
	ds_bpermute_b32 v54, v133, v52
	v_mul_f32_e32 v58, v84, v84
	v_mul_f32_e32 v62, v85, v85
	v_pk_fma_f32 v[140:141], v[126:127], v[126:127], v[56:57] op_sel_hi:[1,1,0]
	v_mov_b32_e32 v67, v58
	v_mov_b32_e32 v141, v62
	v_pk_add_f32 v[66:67], v[66:67], v[140:141]
	v_mov_b32_e32 v74, v77
	v_pk_add_f32 v[46:47], v[46:47], v[66:67]
	s_waitcnt lgkmcnt(0)
	v_pk_add_f32 v[66:67], v[52:53], v[54:55]
	v_mov_b32_e32 v52, v46
	v_mov_b32_e32 v53, v128
	v_mov_b32_e32 v128, v47
	ds_bpermute_b32 v141, v134, v67
	ds_bpermute_b32 v140, v134, v66
	v_pk_add_f32 v[46:47], v[52:53], v[128:129]
	ds_bpermute_b32 v129, v130, v47
	ds_bpermute_b32 v128, v130, v46
	s_waitcnt vmcnt(0)
	s_nop 1
	v_mov_b32_e32 v52, v192
	v_mov_b32_e32 v53, v193
	v_mov_b32_e32 v54, v194
	v_mov_b32_e32 v55, v195
	s_waitcnt lgkmcnt(2)
	v_pk_add_f32 v[44:45], v[66:67], v[140:141]
	ds_bpermute_b32 v67, v135, v45
	ds_bpermute_b32 v66, v135, v44
	s_waitcnt lgkmcnt(2)
	v_pk_add_f32 v[46:47], v[46:47], v[128:129]
	ds_bpermute_b32 v129, v131, v47
	ds_bpermute_b32 v128, v131, v46
	s_nop 1
	v_mov_b32_e32 v140, v196
	v_mov_b32_e32 v141, v197
	v_mov_b32_e32 v142, v198
	v_mov_b32_e32 v143, v199
	s_waitcnt lgkmcnt(2)
	v_pk_add_f32 v[44:45], v[44:45], v[66:67]
	v_mov_b32_e32 v80, v83
	v_pk_fma_f32 v[150:151], v[44:45], s[44:45], v[148:149] op_sel_hi:[1,0,0]
	s_waitcnt lgkmcnt(0)
	v_pk_add_f32 v[44:45], v[46:47], v[128:129]
	ds_bpermute_b32 v47, v132, v45
	ds_bpermute_b32 v46, v132, v44
	v_mul_f32_e32 v56, 0x4b800000, v151
	v_cmp_gt_f32_e32 vcc, s3, v151
	s_waitcnt lgkmcnt(0)
	v_pk_add_f32 v[128:129], v[44:45], v[46:47]
	ds_bpermute_b32 v145, v133, v129
	ds_bpermute_b32 v144, v133, v128
	v_cndmask_b32_e32 v56, v151, v56, vcc
	v_rsq_f32_e32 v56, v56
	s_nop 1
	v_mov_b32_e32 v44, v200
	v_mov_b32_e32 v45, v201
	v_mov_b32_e32 v46, v202
	v_mov_b32_e32 v47, v203
	s_nop 0
	s_nop 1
	v_mov_b32_e32 v64, v204
	v_mov_b32_e32 v65, v205
	v_mov_b32_e32 v66, v206
	v_mov_b32_e32 v67, v207
	s_waitcnt lgkmcnt(0)
	v_pk_add_f32 v[128:129], v[128:129], v[144:145]
	ds_bpermute_b32 v153, v134, v129
	ds_bpermute_b32 v152, v134, v128
	v_mul_f32_e32 v58, 0x45800000, v56
	v_cndmask_b32_e32 v56, v56, v58, vcc
	v_mul_f32_e32 v58, 0x4b800000, v150
	v_cmp_gt_f32_e32 vcc, s3, v150
	s_waitcnt lgkmcnt(0)
	v_pk_add_f32 v[128:129], v[128:129], v[152:153]
	ds_bpermute_b32 v153, v135, v129
	ds_bpermute_b32 v152, v135, v128
	v_cndmask_b32_e32 v58, v150, v58, vcc
	v_rsq_f32_e32 v58, v58
	v_pk_mul_f32 v[100:101], v[56:57], v[100:101] op_sel_hi:[0,1]
	v_pk_mul_f32 v[102:103], v[56:57], v[102:103] op_sel_hi:[0,1]
	s_waitcnt lgkmcnt(0)
; __device__ __forceinline__ void ew_post(const bf16* Y, const float* xin, float* xout, const float* gpost, const float* gnext, bf16* H, int gw, int ngw, int lane) {
;     ...
;         for (int j = 0; j < 4; ++j) { const f32x4 g = *((const f32x4*)gpost + lane + 64 * j);
; #pragma unroll
;             for (int q = 0; q < EW_NR; ++q) { xv[q][j] = xv[q][j] + y[q][j] * rstd[q] * g; __builtin_nontemporal_store(xv[q][j], (f32x4*)(xout + (size_t)(m0 + q) * DM) + lane + 64 * j);
;                 s2[q] += (xv[q][j].x * xv[q][j].x + xv[q][j].y * xv[q][j].y) + (xv[q][j].z * xv[q][j].z + xv[q][j].w * xv[q][j].w); } }
	v_pk_add_f32 v[128:129], v[128:129], v[152:153]
	v_pk_fma_f32 v[22:23], v[102:103], v[138:139], v[22:23]
	v_pk_fma_f32 v[128:129], v[128:129], s[44:45], v[148:149] op_sel_hi:[1,0,0]
	v_pk_fma_f32 v[20:21], v[100:101], v[136:137], v[20:21]
	v_mul_f32_e32 v62, 0x4b800000, v129
	v_cmp_gt_f32_e64 s[4:5], s3, v129
	s_nop 1
	v_mov_b32_e32 v100, v208
	v_mov_b32_e32 v101, v209
	v_mov_b32_e32 v102, v210
	v_mov_b32_e32 v103, v211
	s_nop 1
	v_mov_b32_e32 v144, v212
	v_mov_b32_e32 v145, v213
	v_mov_b32_e32 v146, v214
	v_mov_b32_e32 v147, v215
	v_cndmask_b32_e64 v62, v129, v62, s[4:5]
	v_rsq_f32_e32 v62, v62
	s_nop 1
	v_mov_b32_e32 v148, v216
	v_mov_b32_e32 v149, v217
	v_mov_b32_e32 v150, v218
	v_mov_b32_e32 v151, v219
	v_mul_f32_e32 v36, 0x45800000, v58
	v_cndmask_b32_e32 v58, v58, v36, vcc
	v_mul_f32_e32 v36, 0x45800000, v62
	v_cndmask_b32_e64 v76, v62, v36, s[4:5]
	v_mul_f32_e32 v36, 0x4b800000, v128
	v_cmp_gt_f32_e32 vcc, s3, v128
	v_pk_mul_f32 v[50:51], v[56:57], v[50:51] op_sel_hi:[0,1]
	v_pk_mul_f32 v[48:49], v[56:57], v[48:49] op_sel_hi:[0,1]
	v_cndmask_b32_e32 v36, v128, v36, vcc
	v_rsq_f32_e32 v62, v36
	v_pk_mul_f32 v[36:37], v[58:59], v[110:111] op_sel_hi:[0,1]
	v_pk_fma_f32 v[24:25], v[36:37], v[136:137], v[24:25]
	v_lshl_add_u64 v[128:129], s[10:11], 0, v[178:179]
	v_mul_f32_e32 v36, 0x45800000, v62
	v_pk_mul_f32 v[110:111], v[58:59], v[112:113] op_sel_hi:[0,1]
	v_cndmask_b32_e32 v82, v62, v36, vcc
	v_pk_mul_f32 v[36:37], v[76:77], v[118:119] op_sel_hi:[0,1]
	v_add_co_u32_e32 v118, vcc, s23, v128
	v_pk_fma_f32 v[26:27], v[110:111], v[138:139], v[26:27]
	v_pk_mul_f32 v[110:111], v[76:77], v[120:121] op_sel_hi:[0,1]
	v_addc_co_u32_e32 v119, vcc, 0, v129, vcc
	v_pk_fma_f32 v[34:35], v[138:139], v[110:111], v[34:35]
	v_pk_fma_f32 v[32:33], v[136:137], v[36:37], v[32:33]
	v_pk_mul_f32 v[36:37], v[82:83], v[122:123] op_sel_hi:[0,1]
	v_pk_mul_f32 v[110:111], v[82:83], v[124:125] op_sel_hi:[0,1]
	v_add_co_u32_e32 v120, vcc, s24, v128
	v_pk_fma_f32 v[30:31], v[138:139], v[110:111], v[30:31]
	v_pk_fma_f32 v[28:29], v[136:137], v[36:37], v[28:29]
	v_addc_co_u32_e32 v121, vcc, 0, v129, vcc
	global_store_dwordx4 v[128:129], v[20:23], off sc0 sc1 nt
	global_store_dwordx4 v[118:119], v[24:27], off offset:-4096 sc0 sc1 nt
	global_store_dwordx4 v[118:119], v[32:35], off sc0 sc1 nt
	global_store_dwordx4 v[120:121], v[28:31], off sc0 sc1 nt
	s_nop 1
	v_mov_b32_e32 v110, v160
	v_mov_b32_e32 v111, v161
	v_mov_b32_e32 v112, v162
	v_mov_b32_e32 v113, v163
	v_mov_b32_e32 v36, v39
	v_mov_b32_e32 v37, v41
	v_pk_mul_f32 v[36:37], v[56:57], v[36:37] op_sel_hi:[0,1]
	v_mov_b32_e32 v39, v40
	v_pk_mul_f32 v[38:39], v[56:57], v[38:39] op_sel_hi:[0,1]
	v_mov_b32_e32 v40, v115
	v_mov_b32_e32 v41, v117
	v_mov_b32_e32 v115, v116
	v_add_co_u32_e32 v122, vcc, s22, v128
	v_mov_b32_e32 v62, v87
	s_nop 0
	v_addc_co_u32_e32 v123, vcc, 0, v129, vcc
	v_pk_mul_f32 v[86:87], v[56:57], v[88:89] op_sel_hi:[0,1]
	v_pk_mul_f32 v[62:63], v[56:57], v[62:63] op_sel_hi:[0,1]
	v_mov_b32_e32 v56, v59
	v_pk_mul_f32 v[88:89], v[58:59], v[60:61] op_sel_hi:[0,1]
	s_andn2_b64 vcc, exec, s[30:31]
	v_pk_fma_f32 v[14:15], v[36:37], v[112:113], v[14:15]
	v_mov_b32_e32 v36, v43
	v_mov_b32_e32 v37, v95
	v_pk_mul_f32 v[36:37], v[58:59], v[36:37] op_sel_hi:[0,1]
	v_mov_b32_e32 v43, v94
	v_pk_fma_f32 v[12:13], v[38:39], v[110:111], v[12:13]
	v_pk_mul_f32 v[38:39], v[58:59], v[42:43] op_sel_hi:[0,1]
	v_pk_fma_f32 v[18:19], v[36:37], v[112:113], v[18:19]
	v_mov_b32_e32 v36, v105
	v_mov_b32_e32 v37, v107
	v_mov_b32_e32 v105, v106
	v_pk_fma_f32 v[16:17], v[38:39], v[110:111], v[16:17]
	v_pk_mul_f32 v[38:39], v[76:77], v[36:37] op_sel_hi:[0,1]
	v_pk_mul_f32 v[36:37], v[76:77], v[104:105] op_sel_hi:[0,1]
	v_pk_mul_f32 v[42:43], v[82:83], v[40:41] op_sel_hi:[0,1]
	v_pk_mul_f32 v[40:41], v[82:83], v[114:115] op_sel_hi:[0,1]
	v_pk_fma_f32 v[36:37], v[110:111], v[36:37], v[140:141]
	v_pk_fma_f32 v[38:39], v[112:113], v[38:39], v[142:143]
	v_pk_fma_f32 v[40:41], v[110:111], v[40:41], v[100:101]
	v_pk_fma_f32 v[42:43], v[112:113], v[42:43], v[102:103]
	global_store_dwordx4 v[128:129], v[12:15], off offset:1024 sc0 sc1 nt
	global_store_dwordx4 v[122:123], v[16:19], off offset:1024 sc0 sc1 nt
	global_store_dwordx4 v[118:119], v[36:39], off offset:1024 sc0 sc1 nt
	global_store_dwordx4 v[120:121], v[40:43], off offset:1024 sc0 sc1 nt
	s_nop 1
	v_mov_b32_e32 v100, v164
	v_mov_b32_e32 v101, v165
	v_mov_b32_e32 v102, v166
	v_mov_b32_e32 v103, v167
	v_pk_fma_f32 v[4:5], v[48:49], v[100:101], v[4:5]
	v_pk_fma_f32 v[6:7], v[50:51], v[102:103], v[6:7]
	v_pk_mul_f32 v[48:49], v[58:59], v[92:93] op_sel_hi:[0,1]
	v_pk_mul_f32 v[50:51], v[58:59], v[90:91] op_sel_hi:[0,1]
	v_pk_fma_f32 v[8:9], v[50:51], v[100:101], v[8:9]
	v_pk_fma_f32 v[10:11], v[48:49], v[102:103], v[10:11]
	v_pk_mul_f32 v[48:49], v[76:77], v[98:99] op_sel_hi:[0,1]
	v_pk_mul_f32 v[50:51], v[76:77], v[96:97] op_sel_hi:[0,1]
	v_pk_fma_f32 v[44:45], v[50:51], v[100:101], v[44:45]
	v_pk_fma_f32 v[46:47], v[48:49], v[102:103], v[46:47]
	v_pk_mul_f32 v[50:51], v[82:83], v[126:127] op_sel_hi:[0,1]
	v_pk_mul_f32 v[48:49], v[82:83], v[108:109] op_sel_hi:[0,1]
	v_pk_fma_f32 v[48:49], v[100:101], v[48:49], v[144:145]
	v_pk_fma_f32 v[50:51], v[102:103], v[50:51], v[146:147]
	global_store_dwordx4 v[128:129], v[4:7], off offset:2048 sc0 sc1 nt
	global_store_dwordx4 v[122:123], v[8:11], off offset:2048 sc0 sc1 nt
	global_store_dwordx4 v[118:119], v[44:47], off offset:2048 sc0 sc1 nt
	global_store_dwordx4 v[120:121], v[48:51], off offset:2048 sc0 sc1 nt
	s_nop 1
	v_mov_b32_e32 v90, v168
	v_mov_b32_e32 v91, v169
	v_mov_b32_e32 v92, v170
	v_mov_b32_e32 v93, v171
	v_pk_fma_f32 v[60:61], v[62:63], v[90:91], v[0:1]
	v_pk_mul_f32 v[0:1], v[58:59], v[56:57] op_sel_hi:[0,1]
	v_pk_fma_f32 v[62:63], v[86:87], v[92:93], v[2:3]
	v_pk_fma_f32 v[56:57], v[0:1], v[90:91], v[52:53]
	v_pk_mul_f32 v[0:1], v[76:77], v[78:79] op_sel_hi:[0,1]
	v_pk_mul_f32 v[2:3], v[76:77], v[74:75] op_sel_hi:[0,1]
	v_pk_fma_f32 v[58:59], v[88:89], v[92:93], v[54:55]
	v_pk_fma_f32 v[52:53], v[2:3], v[90:91], v[64:65]
	v_pk_fma_f32 v[54:55], v[0:1], v[92:93], v[66:67]
	v_pk_mul_f32 v[2:3], v[82:83], v[84:85] op_sel_hi:[0,1]
	v_pk_mul_f32 v[0:1], v[82:83], v[80:81] op_sel_hi:[0,1]
	v_pk_fma_f32 v[0:1], v[0:1], v[90:91], v[148:149]
	v_pk_fma_f32 v[2:3], v[2:3], v[92:93], v[150:151]
	global_store_dwordx4 v[128:129], v[60:63], off offset:3072 sc0 sc1 nt
	global_store_dwordx4 v[122:123], v[56:59], off offset:3072 sc0 sc1 nt
	global_store_dwordx4 v[118:119], v[52:55], off offset:3072 sc0 sc1 nt
	global_store_dwordx4 v[120:121], v[0:3], off offset:3072 sc0 sc1 nt
	s_cbranch_vccnz .LBB0_208
; __device__ __forceinline__ void ew_post(const bf16* Y, const float* xin, float* xout, const float* gpost, const float* gnext, bf16* H, int gw, int ngw, int lane) {
;     ...
;                 s2[q] += (xv[q][j].x * xv[q][j].x + xv[q][j].y * xv[q][j].y) + (xv[q][j].z * xv[q][j].z + xv[q][j].w * xv[q][j].w); } }
;         if (gnext) {
;             float r2[EW_NR];
; #pragma unroll
;             for (int q = 0; q < EW_NR; ++q) r2[q] = rsqrtf(wave_sum(s2[q]) * (1.f / DM) + RMS_EPS);
	v_pk_mul_f32 v[64:65], v[30:31], v[30:31]
	v_pk_mul_f32 v[66:67], v[28:29], v[28:29]
	v_mul_f32_e32 v78, v1, v1
	v_pk_mov_b32 v[74:75], v[66:67], v[64:65] op_sel:[1,0]
	v_mov_b32_e32 v67, v65
	v_pk_add_f32 v[64:65], v[74:75], v[66:67]
	v_pk_mul_f32 v[66:67], v[42:43], v[42:43]
	v_pk_mul_f32 v[74:75], v[40:41], v[40:41]
	v_mul_f32_e32 v79, v2, v2
	v_pk_mov_b32 v[76:77], v[74:75], v[66:67] op_sel:[1,0]
	v_mov_b32_e32 v75, v67
	v_pk_add_f32 v[66:67], v[76:77], v[74:75]
	v_mul_f32_e32 v74, v49, v49
	v_mul_f32_e32 v76, v0, v0
	v_pk_fma_f32 v[74:75], v[48:49], v[48:49], v[74:75] op_sel_hi:[1,1,0]
	v_mul_f32_e32 v80, v3, v3
	v_mov_b32_e32 v75, v76
	v_mul_f32_e32 v76, v51, v51
	v_pk_fma_f32 v[76:77], v[50:51], v[50:51], v[76:77] op_sel_hi:[1,1,0]
	v_pk_add_f32 v[64:65], v[64:65], v[64:65] op_sel:[0,1] op_sel_hi:[1,0]
	v_pk_add_f32 v[66:67], v[66:67], v[66:67] op_sel:[0,1] op_sel_hi:[1,0]
	v_mov_b32_e32 v77, v78
	v_mov_b32_e32 v65, v79
	v_mov_b32_e32 v67, v80
	v_pk_add_f32 v[74:75], v[74:75], v[76:77]
	v_pk_add_f32 v[64:65], v[64:65], v[66:67]
	v_pk_mul_f32 v[66:67], v[34:35], v[34:35]
	v_pk_add_f32 v[64:65], v[74:75], v[64:65]
	v_pk_mul_f32 v[74:75], v[32:33], v[32:33]
	v_mul_f32_e32 v86, v53, v53
	v_pk_mov_b32 v[76:77], v[74:75], v[66:67] op_sel:[1,0]
	v_mov_b32_e32 v75, v67
	v_pk_add_f32 v[66:67], v[76:77], v[74:75]
	v_pk_mul_f32 v[74:75], v[38:39], v[38:39]
	v_pk_mul_f32 v[76:77], v[36:37], v[36:37]
	v_pk_add_f32 v[66:67], v[66:67], v[66:67] op_sel:[0,1] op_sel_hi:[1,0]
	v_pk_mov_b32 v[78:79], v[76:77], v[74:75] op_sel:[1,0]
	v_mov_b32_e32 v77, v75
	v_pk_add_f32 v[74:75], v[78:79], v[76:77]
	v_mul_f32_e32 v76, v52, v52
	v_mov_b32_e32 v67, v76
	v_pk_mul_f32 v[76:77], v[26:27], v[26:27]
	v_pk_mul_f32 v[78:79], v[24:25], v[24:25]
	v_mul_f32_e32 v87, v54, v54
	v_pk_mov_b32 v[80:81], v[78:79], v[76:77] op_sel:[1,0]
	v_mov_b32_e32 v79, v77
	v_pk_add_f32 v[76:77], v[80:81], v[78:79]
	v_pk_mul_f32 v[78:79], v[18:19], v[18:19]
	v_pk_mul_f32 v[80:81], v[16:17], v[16:17]
	v_pk_add_f32 v[76:77], v[76:77], v[76:77] op_sel:[0,1] op_sel_hi:[1,0]
	v_pk_mov_b32 v[82:83], v[80:81], v[78:79] op_sel:[1,0]
	v_mov_b32_e32 v81, v79
	v_pk_add_f32 v[78:79], v[82:83], v[80:81]
	v_mul_f32_e32 v80, v56, v56
	v_mul_f32_e32 v81, v57, v57
	v_pk_add_f32 v[78:79], v[78:79], v[78:79] op_sel:[0,1] op_sel_hi:[1,0]
	v_mov_b32_e32 v77, v80
	v_mov_b32_e32 v79, v81
	v_pk_add_f32 v[76:77], v[76:77], v[78:79]
	v_mul_f32_e32 v78, v9, v9
	v_mul_f32_e32 v80, v11, v11
	v_mul_f32_e32 v82, v58, v58
	v_mul_f32_e32 v83, v59, v59
	v_pk_fma_f32 v[78:79], v[8:9], v[8:9], v[78:79] op_sel_hi:[1,1,0]
	v_pk_fma_f32 v[80:81], v[10:11], v[10:11], v[80:81] op_sel_hi:[1,1,0]
	v_mov_b32_e32 v79, v82
	v_mov_b32_e32 v81, v83
	v_pk_add_f32 v[78:79], v[78:79], v[80:81]
	v_pk_mul_f32 v[80:81], v[20:21], v[20:21]
	v_pk_add_f32 v[76:77], v[76:77], v[78:79]
	v_pk_mul_f32 v[78:79], v[22:23], v[22:23]
	v_mul_f32_e32 v88, v55, v55
	v_pk_mov_b32 v[82:83], v[80:81], v[78:79] op_sel:[1,0]
	v_mov_b32_e32 v81, v79
	v_pk_add_f32 v[78:79], v[82:83], v[80:81]
	v_pk_mul_f32 v[80:81], v[14:15], v[14:15]
	v_pk_mul_f32 v[82:83], v[12:13], v[12:13]
	v_pk_add_f32 v[78:79], v[78:79], v[78:79] op_sel:[0,1] op_sel_hi:[1,0]
	v_pk_mov_b32 v[84:85], v[82:83], v[80:81] op_sel:[1,0]
	v_mov_b32_e32 v83, v81
	v_pk_add_f32 v[80:81], v[84:85], v[82:83]
	v_mul_f32_e32 v82, v60, v60
	v_mul_f32_e32 v83, v61, v61
	v_pk_add_f32 v[80:81], v[80:81], v[80:81] op_sel:[0,1] op_sel_hi:[1,0]
	v_mov_b32_e32 v79, v82
	v_mov_b32_e32 v81, v83
	v_pk_add_f32 v[78:79], v[78:79], v[80:81]
	v_mul_f32_e32 v80, v5, v5
	v_mul_f32_e32 v82, v7, v7
	v_mul_f32_e32 v84, v62, v62
	v_mul_f32_e32 v85, v63, v63
	v_pk_fma_f32 v[80:81], v[4:5], v[4:5], v[80:81] op_sel_hi:[1,1,0]
	v_pk_fma_f32 v[82:83], v[6:7], v[6:7], v[82:83] op_sel_hi:[1,1,0]
	v_mov_b32_e32 v81, v84
	v_mov_b32_e32 v83, v85
	v_pk_add_f32 v[80:81], v[80:81], v[82:83]
	v_pk_add_f32 v[82:83], v[74:75], v[74:75] op_sel:[0,1] op_sel_hi:[1,0]
	v_pk_add_f32 v[78:79], v[78:79], v[80:81]
	v_mov_b32_e32 v80, v76
	v_mov_b32_e32 v81, v78
	v_mov_b32_e32 v78, v77
	s_nop 1
	v_mov_b32_e32 v74, v232
	v_mov_b32_e32 v75, v233
	v_mov_b32_e32 v76, v234
	v_mov_b32_e32 v77, v235
	v_pk_add_f32 v[78:79], v[80:81], v[78:79]
	v_mov_b32_e32 v83, v86
	ds_bpermute_b32 v81, v130, v79
	ds_bpermute_b32 v80, v130, v78
	v_pk_add_f32 v[66:67], v[66:67], v[82:83]
	v_mul_f32_e32 v82, v45, v45
	v_mul_f32_e32 v84, v47, v47
	v_pk_fma_f32 v[82:83], v[44:45], v[44:45], v[82:83] op_sel_hi:[1,1,0]
	v_pk_fma_f32 v[84:85], v[46:47], v[46:47], v[84:85] op_sel_hi:[1,1,0]
	v_mov_b32_e32 v83, v87
	v_mov_b32_e32 v85, v88
	v_pk_add_f32 v[82:83], v[82:83], v[84:85]
	s_waitcnt lgkmcnt(0)
	v_pk_add_f32 v[78:79], v[78:79], v[80:81]
	v_pk_add_f32 v[66:67], v[66:67], v[82:83]
	v_mov_b32_e32 v82, v64
	v_mov_b32_e32 v83, v66
	v_mov_b32_e32 v66, v65
	ds_bpermute_b32 v81, v131, v79
	ds_bpermute_b32 v80, v131, v78
	v_pk_add_f32 v[64:65], v[82:83], v[66:67]
	ds_bpermute_b32 v67, v130, v65
	ds_bpermute_b32 v66, v130, v64
	s_waitcnt lgkmcnt(2)
	v_pk_add_f32 v[78:79], v[78:79], v[80:81]
	ds_bpermute_b32 v81, v132, v79
	ds_bpermute_b32 v80, v132, v78
	s_waitcnt lgkmcnt(2)
	v_pk_add_f32 v[64:65], v[64:65], v[66:67]
	ds_bpermute_b32 v67, v131, v65
	ds_bpermute_b32 v66, v131, v64
	s_waitcnt lgkmcnt(2)
	v_pk_add_f32 v[78:79], v[78:79], v[80:81]
	ds_bpermute_b32 v81, v133, v79
	ds_bpermute_b32 v80, v133, v78
	s_waitcnt lgkmcnt(2)
	v_pk_add_f32 v[64:65], v[64:65], v[66:67]
	ds_bpermute_b32 v67, v132, v65
	ds_bpermute_b32 v66, v132, v64
	s_waitcnt lgkmcnt(2)
	v_pk_add_f32 v[78:79], v[78:79], v[80:81]
	ds_bpermute_b32 v81, v134, v79
	ds_bpermute_b32 v80, v134, v78
	s_waitcnt lgkmcnt(2)
; __device__ __forceinline__ void ew_post(const bf16* Y, const float* xin, float* xout, const float* gpost, const float* gnext, bf16* H, int gw, int ngw, int lane) {
;     ...
;             for (int q = 0; q < EW_NR; ++q) r2[q] = rsqrtf(wave_sum(s2[q]) * (1.f / DM) + RMS_EPS);
	v_pk_add_f32 v[64:65], v[64:65], v[66:67]
	ds_bpermute_b32 v67, v133, v65
	ds_bpermute_b32 v66, v133, v64
	s_waitcnt lgkmcnt(2)
	v_pk_add_f32 v[78:79], v[78:79], v[80:81]
	ds_bpermute_b32 v81, v135, v79
	ds_bpermute_b32 v80, v135, v78
	s_waitcnt lgkmcnt(2)
	v_pk_add_f32 v[64:65], v[64:65], v[66:67]
	ds_bpermute_b32 v67, v134, v65
	ds_bpermute_b32 v66, v134, v64
	s_waitcnt lgkmcnt(2)
	v_pk_add_f32 v[78:79], v[78:79], v[80:81]
	v_mov_b64_e32 v[80:81], s[26:27]
	v_pk_fma_f32 v[78:79], v[78:79], s[44:45], v[80:81] op_sel_hi:[1,0,0]
	s_waitcnt lgkmcnt(0)
	v_pk_add_f32 v[64:65], v[64:65], v[66:67]
	v_mul_f32_e32 v82, 0x4b800000, v79
	v_cmp_gt_f32_e32 vcc, s3, v79
	ds_bpermute_b32 v67, v135, v65
	ds_bpermute_b32 v66, v135, v64
	v_cndmask_b32_e32 v79, v79, v82, vcc
	v_rsq_f32_e32 v79, v79
	v_mul_f32_e32 v82, 0x4b800000, v78
	v_cmp_gt_f32_e64 s[4:5], s3, v78
	s_waitcnt lgkmcnt(0)
; __device__ __forceinline__ unsigned pk2(float lo, float hi) { f32v2 v = {lo, hi}; bf16v2 r = __builtin_convertvector(v, bf16v2); return __builtin_bit_cast(unsigned, r); }
; __device__ __forceinline__ void ew_post(const bf16* Y, const float* xin, float* xout, const float* gpost, const float* gnext, bf16* H, int gw, int ngw, int lane) {
;     ...
;             for (int q = 0; q < EW_NR; ++q) r2[q] = rsqrtf(wave_sum(s2[q]) * (1.f / DM) + RMS_EPS);
; #pragma unroll
;             for (int j = 0; j < 4; ++j) { const f32x4 g = *((const f32x4*)gnext + lane + 64 * j);
; #pragma unroll
;                 for (int q = 0; q < EW_NR; ++q) { v2u w; w.x = pk2(xv[q][j].x * r2[q] * g.x, xv[q][j].y * r2[q] * g.y); w.y = pk2(xv[q][j].z * r2[q] * g.z, xv[q][j].w * r2[q] * g.w);
;                     *((v2u*)(H + (size_t)(m0 + q) * DM) + lane + 64 * j) = w; } }
	v_pk_add_f32 v[64:65], v[64:65], v[66:67]
	v_cndmask_b32_e64 v78, v78, v82, s[4:5]
	v_rsq_f32_e32 v82, v78
	v_mul_f32_e32 v78, 0x45800000, v79
	v_pk_fma_f32 v[64:65], v[64:65], s[44:45], v[80:81] op_sel_hi:[1,0,0]
	v_cndmask_b32_e32 v78, v79, v78, vcc
	v_mul_f32_e32 v66, 0x4b800000, v65
	v_cmp_gt_f32_e32 vcc, s3, v65
	v_mul_f32_e32 v79, 0x45800000, v82
	v_cmp_gt_f32_e64 s[6:7], s3, v64
	v_cndmask_b32_e32 v65, v65, v66, vcc
	v_rsq_f32_e32 v65, v65
	v_mul_f32_e32 v66, 0x4b800000, v64
	v_pk_mul_f32 v[20:21], v[20:21], v[78:79] op_sel_hi:[1,0]
	v_pk_mul_f32 v[22:23], v[22:23], v[78:79] op_sel_hi:[1,0]
	v_mul_f32_e32 v67, 0x45800000, v65
	v_cndmask_b32_e64 v64, v64, v66, s[6:7]
	v_cndmask_b32_e64 v66, v82, v79, s[4:5]
	v_cndmask_b32_e32 v80, v65, v67, vcc
	v_pk_mul_f32 v[20:21], v[20:21], v[74:75]
	v_pk_mul_f32 v[22:23], v[22:23], v[76:77]
	v_add_co_u32_e32 v82, vcc, s20, v72
	v_cvt_pk_bf16_f32 v20, v20, v21
	v_cvt_pk_bf16_f32 v21, v22, v23
	v_addc_co_u32_e32 v83, vcc, -1, v73, vcc
	v_rsq_f32_e32 v64, v64
	global_store_dwordx2 v[82:83], v[20:21], off offset:-3584
	v_pk_mul_f32 v[20:21], v[24:25], v[66:67] op_sel_hi:[1,0]
	v_pk_mul_f32 v[22:23], v[26:27], v[66:67] op_sel_hi:[1,0]
	v_pk_mul_f32 v[20:21], v[20:21], v[74:75]
	v_pk_mul_f32 v[22:23], v[22:23], v[76:77]
	v_cvt_pk_bf16_f32 v20, v20, v21
	v_cvt_pk_bf16_f32 v21, v22, v23
	global_store_dwordx2 v[82:83], v[20:21], off offset:-1536
	v_pk_mul_f32 v[20:21], v[32:33], v[80:81] op_sel_hi:[1,0]
	v_pk_mul_f32 v[22:23], v[34:35], v[80:81] op_sel_hi:[1,0]
	v_mul_f32_e32 v65, 0x45800000, v64
	v_pk_mul_f32 v[20:21], v[74:75], v[20:21]
	v_pk_mul_f32 v[22:23], v[76:77], v[22:23]
	v_add_co_u32_e32 v24, vcc, s21, v72
	v_cndmask_b32_e64 v64, v64, v65, s[6:7]
	v_cvt_pk_bf16_f32 v20, v20, v21
	v_cvt_pk_bf16_f32 v21, v22, v23
	v_addc_co_u32_e32 v25, vcc, -1, v73, vcc
	global_store_dwordx2 v[24:25], v[20:21], off offset:-3584
	v_pk_mul_f32 v[20:21], v[28:29], v[64:65] op_sel_hi:[1,0]
	v_pk_mul_f32 v[22:23], v[30:31], v[64:65] op_sel_hi:[1,0]
	v_pk_mul_f32 v[20:21], v[74:75], v[20:21]
	v_pk_mul_f32 v[22:23], v[76:77], v[22:23]
	v_cvt_pk_bf16_f32 v20, v20, v21
	v_cvt_pk_bf16_f32 v21, v22, v23
	global_store_dwordx2 v[24:25], v[20:21], off offset:-1536
	s_nop 1
	v_mov_b32_e32 v20, v236
	v_mov_b32_e32 v21, v237
	v_mov_b32_e32 v22, v238
	v_mov_b32_e32 v23, v239
	v_pk_mul_f32 v[12:13], v[12:13], v[78:79] op_sel_hi:[1,0]
	v_pk_mul_f32 v[14:15], v[14:15], v[78:79] op_sel_hi:[1,0]
	v_pk_mul_f32 v[4:5], v[4:5], v[78:79] op_sel_hi:[1,0]
	v_pk_mul_f32 v[6:7], v[6:7], v[78:79] op_sel_hi:[1,0]
	v_pk_mul_f32 v[0:1], v[0:1], v[64:65] op_sel_hi:[1,0]
	v_pk_mul_f32 v[2:3], v[2:3], v[64:65] op_sel_hi:[1,0]
	v_pk_mul_f32 v[12:13], v[12:13], v[20:21]
	v_pk_mul_f32 v[14:15], v[14:15], v[22:23]
	v_cvt_pk_bf16_f32 v12, v12, v13
	v_cvt_pk_bf16_f32 v13, v14, v15
	global_store_dwordx2 v[82:83], v[12:13], off offset:-3072
	v_pk_mul_f32 v[12:13], v[16:17], v[66:67] op_sel_hi:[1,0]
	v_pk_mul_f32 v[14:15], v[18:19], v[66:67] op_sel_hi:[1,0]
	v_pk_mul_f32 v[12:13], v[12:13], v[20:21]
	v_pk_mul_f32 v[14:15], v[14:15], v[22:23]
	v_cvt_pk_bf16_f32 v12, v12, v13
	v_cvt_pk_bf16_f32 v13, v14, v15
	global_store_dwordx2 v[82:83], v[12:13], off offset:-1024
	v_pk_mul_f32 v[12:13], v[36:37], v[80:81] op_sel_hi:[1,0]
	v_pk_mul_f32 v[14:15], v[38:39], v[80:81] op_sel_hi:[1,0]
	v_pk_mul_f32 v[12:13], v[12:13], v[20:21]
	v_pk_mul_f32 v[14:15], v[14:15], v[22:23]
	v_cvt_pk_bf16_f32 v12, v12, v13
	v_cvt_pk_bf16_f32 v13, v14, v15
	global_store_dwordx2 v[24:25], v[12:13], off offset:-3072
	v_pk_mul_f32 v[12:13], v[40:41], v[64:65] op_sel_hi:[1,0]
	v_pk_mul_f32 v[14:15], v[42:43], v[64:65] op_sel_hi:[1,0]
	v_pk_mul_f32 v[12:13], v[20:21], v[12:13]
	v_pk_mul_f32 v[14:15], v[22:23], v[14:15]
	v_cvt_pk_bf16_f32 v12, v12, v13
	v_cvt_pk_bf16_f32 v13, v14, v15
	global_store_dwordx2 v[24:25], v[12:13], off offset:-1024
	s_nop 1
	v_mov_b32_e32 v12, v240
	v_mov_b32_e32 v13, v241
	v_mov_b32_e32 v14, v242
	v_mov_b32_e32 v15, v243
	v_pk_mul_f32 v[16:17], v[52:53], v[80:81] op_sel_hi:[1,0]
	v_pk_mul_f32 v[18:19], v[54:55], v[80:81] op_sel_hi:[1,0]
	v_pk_mul_f32 v[4:5], v[4:5], v[12:13]
	v_pk_mul_f32 v[6:7], v[6:7], v[14:15]
	v_cvt_pk_bf16_f32 v4, v4, v5
	v_cvt_pk_bf16_f32 v5, v6, v7
	global_store_dwordx2 v[82:83], v[4:5], off offset:-2560
	v_pk_mul_f32 v[4:5], v[8:9], v[66:67] op_sel_hi:[1,0]
	v_pk_mul_f32 v[6:7], v[10:11], v[66:67] op_sel_hi:[1,0]
	v_pk_mul_f32 v[4:5], v[4:5], v[12:13]
	v_pk_mul_f32 v[6:7], v[6:7], v[14:15]
	v_cvt_pk_bf16_f32 v4, v4, v5
	v_cvt_pk_bf16_f32 v5, v6, v7
	global_store_dwordx2 v[82:83], v[4:5], off offset:-512
	v_pk_mul_f32 v[4:5], v[44:45], v[80:81] op_sel_hi:[1,0]
	v_pk_mul_f32 v[6:7], v[46:47], v[80:81] op_sel_hi:[1,0]
	v_pk_mul_f32 v[4:5], v[4:5], v[12:13]
	v_pk_mul_f32 v[6:7], v[6:7], v[14:15]
	v_cvt_pk_bf16_f32 v4, v4, v5
	v_cvt_pk_bf16_f32 v5, v6, v7
	global_store_dwordx2 v[24:25], v[4:5], off offset:-2560
	v_pk_mul_f32 v[4:5], v[48:49], v[64:65] op_sel_hi:[1,0]
	v_pk_mul_f32 v[6:7], v[50:51], v[64:65] op_sel_hi:[1,0]
	v_pk_mul_f32 v[4:5], v[4:5], v[12:13]
	v_pk_mul_f32 v[6:7], v[6:7], v[14:15]
	v_cvt_pk_bf16_f32 v4, v4, v5
	v_cvt_pk_bf16_f32 v5, v6, v7
	global_store_dwordx2 v[24:25], v[4:5], off offset:-512
	s_nop 1
	v_mov_b32_e32 v4, v244
	v_mov_b32_e32 v5, v245
	v_mov_b32_e32 v6, v246
	v_mov_b32_e32 v7, v247
	v_pk_mul_f32 v[8:9], v[60:61], v[78:79] op_sel_hi:[1,0]
	v_pk_mul_f32 v[10:11], v[62:63], v[78:79] op_sel_hi:[1,0]
	v_pk_mul_f32 v[12:13], v[56:57], v[66:67] op_sel_hi:[1,0]
	v_pk_mul_f32 v[14:15], v[58:59], v[66:67] op_sel_hi:[1,0]
	v_pk_mul_f32 v[8:9], v[8:9], v[4:5]
	v_pk_mul_f32 v[10:11], v[10:11], v[6:7]
	v_pk_mul_f32 v[12:13], v[12:13], v[4:5]
	v_pk_mul_f32 v[14:15], v[14:15], v[6:7]
	v_pk_mul_f32 v[16:17], v[16:17], v[4:5]
	v_pk_mul_f32 v[18:19], v[18:19], v[6:7]
	v_pk_mul_f32 v[0:1], v[0:1], v[4:5]
	v_pk_mul_f32 v[2:3], v[2:3], v[6:7]
	v_cvt_pk_bf16_f32 v4, v8, v9
	v_cvt_pk_bf16_f32 v5, v10, v11
	v_cvt_pk_bf16_f32 v6, v12, v13
	v_cvt_pk_bf16_f32 v7, v14, v15
	v_cvt_pk_bf16_f32 v8, v16, v17
	v_cvt_pk_bf16_f32 v9, v18, v19
	v_cvt_pk_bf16_f32 v0, v0, v1
	v_cvt_pk_bf16_f32 v1, v2, v3
	global_store_dwordx2 v[82:83], v[4:5], off offset:-2048
	global_store_dwordx2 v[24:25], v[6:7], off offset:-4096
	global_store_dwordx2 v[24:25], v[8:9], off offset:-2048
	global_store_dwordx2 v[24:25], v[0:1], off
	s_branch .LBB0_208
